# v84 + weight-conversion stores write-through (nt -> sc1) so the release write-back at the layer-0 grid barriers finds no dirty lines
# baseline (speedup 1.0000x reference)
; #define LAS __attribute__((address_space(3)))
; __device__ __forceinline__ unsigned pk2(float lo, float hi) { return pg8::cvt_pk_bf16(lo, hi); }
; __device__ __forceinline__ void tr_load(const TrD& d, int lane, f32x4 (&v)[16]) {
;     const int nblk = d.N / 64, kb = d.item / nblk, nb = d.item % nblk, k0 = 64 * kb, n0 = 64 * nb, lr = lane >> 4, lc = (lane & 15) * 4;
;     const float* src = d.W + (size_t)(k0 + lr) * d.N + n0 + lc;
; #pragma unroll
;     for (int i = 0; i < 16; ++i) v[i] = __builtin_nontemporal_load((const f32x4*)(src + (size_t)(4 * i) * d.N));
; }
; __device__ __forceinline__ void tr_lds_write(LAS float* scr, int lane, const f32x4 (&v)[16]) {
;     const int lr = lane >> 4, lc = (lane & 15) * 4;
; #pragma unroll
;     for (int i = 0; i < 16; ++i) { const int kk = 4 * i + lr; scr[kk * 65 + lc + 0] = v[i][0]; scr[kk * 65 + lc + 1] = v[i][1]; scr[kk * 65 + lc + 2] = v[i][2]; scr[kk * 65 + lc + 3] = v[i][3]; }
;     asm volatile("s_waitcnt lgkmcnt(0)" ::: "memory");
; }
; __device__ __forceinline__ void tr_store(const TrD& d, LAS float* scr, int lane) {
;     const int nblk = d.N / 64, kb = d.item / nblk, nb = d.item % nblk, k0 = 64 * kb, n0 = 64 * nb, c = lane & 7;
; #pragma unroll
;     for (int j = 0; j < 8; ++j) { const int n = (lane >> 3) + 8 * j; const LAS float* s = scr + (8 * c) * 65 + n;
;         v4u o; o.x = pk2(s[0 * 65], s[1 * 65]); o.y = pk2(s[2 * 65], s[3 * 65]); o.z = pk2(s[4 * 65], s[5 * 65]); o.w = pk2(s[6 * 65], s[7 * 65]);
;         int dn = n0 + n; if (d.perm && dn < 1536) { const int f = dn & 127; dn = (dn & ~127) | ((f >> 6) * 64 + 2 * (f & 31) + ((f >> 5) & 1)); }
;         __builtin_nontemporal_store(o, (v4u*)(d.WT + (size_t)dn * d.K + k0 + 8 * c)); }
.LBB0_55:
	s_lshr_b32 s14, s12, 6
	v_cvt_f32_i32_e32 v2, s14
	s_sext_i32_i16 s19, s37
	v_cvt_f32_i32_e32 v3, s19
	s_ashr_i32 s19, s19, 30
	v_rcp_iflag_f32_e32 v4, v2
	s_or_b32 s19, s19, 1
	v_mul_f32_e32 v4, v3, v4
	v_trunc_f32_e32 v4, v4
	v_fma_f32 v3, -v4, v2, v3
	v_cvt_i32_f32_e32 v4, v4
	v_cmp_ge_f32_e64 s[28:29], |v3|, v2
	s_and_b64 s[28:29], s[28:29], exec
	s_cselect_b32 s19, s19, 0
	v_readfirstlane_b32 s28, v4
	s_add_i32 s19, s28, s19
	s_sext_i32_i16 s29, s19
	s_mul_i32 s19, s19, s14
	s_sub_i32 s14, s37, s19
	s_sext_i32_i16 s14, s14
	v_lshl_or_b32 v2, s29, 6, v1
	s_lshl_b32 s28, s14, 6
	v_mul_hi_i32_i24_e32 v3, s12, v2
	v_mul_i32_i24_e32 v2, s12, v2
	v_lshl_add_u64 v[2:3], v[2:3], 2, s[26:27]
	s_ashr_i32 s29, s28, 31
	v_lshl_add_u64 v[2:3], s[28:29], 2, v[2:3]
	v_lshl_add_u64 v[2:3], v[2:3], 0, v[70:71]
	s_lshl_b64 s[26:27], s[12:13], 4
	v_lshl_add_u64 v[4:5], v[2:3], 0, s[26:27]
	global_load_dwordx4 v[62:65], v[2:3], off nt
	global_load_dwordx4 v[58:61], v[4:5], off nt
	v_lshl_add_u64 v[2:3], v[4:5], 0, s[26:27]
	v_lshl_add_u64 v[4:5], v[2:3], 0, s[26:27]
	s_lshr_b32 s14, s18, 6
	global_load_dwordx4 v[54:57], v[2:3], off nt
	global_load_dwordx4 v[50:53], v[4:5], off nt
	v_lshl_add_u64 v[2:3], v[4:5], 0, s[26:27]
	v_cvt_f32_i32_e32 v73, s14
	v_lshl_add_u64 v[4:5], v[2:3], 0, s[26:27]
	global_load_dwordx4 v[42:45], v[2:3], off nt
	global_load_dwordx4 v[38:41], v[4:5], off nt
	v_lshl_add_u64 v[2:3], v[4:5], 0, s[26:27]
	v_lshl_add_u64 v[4:5], v[2:3], 0, s[26:27]
	s_sext_i32_i16 s18, s34
	global_load_dwordx4 v[34:37], v[2:3], off nt
	global_load_dwordx4 v[30:33], v[4:5], off nt
	v_lshl_add_u64 v[2:3], v[4:5], 0, s[26:27]
	v_cvt_f32_i32_e32 v89, s18
	v_rcp_iflag_f32_e32 v90, v73
	global_load_dwordx4 v[26:29], v[2:3], off nt
	v_lshl_add_u64 v[2:3], v[2:3], 0, s[26:27]
	global_load_dwordx4 v[22:25], v[2:3], off nt
	v_lshl_add_u64 v[2:3], v[2:3], 0, s[26:27]
	global_load_dwordx4 v[18:21], v[2:3], off nt
	v_lshl_add_u64 v[2:3], v[2:3], 0, s[26:27]
	global_load_dwordx4 v[14:17], v[2:3], off nt
	v_lshl_add_u64 v[2:3], v[2:3], 0, s[26:27]
	v_mul_f32_e32 v92, v89, v90
	v_lshl_add_u64 v[6:7], v[2:3], 0, s[26:27]
	v_trunc_f32_e32 v92, v92
	v_lshl_add_u64 v[46:47], v[6:7], 0, s[26:27]
	v_cvt_i32_f32_e32 v94, v92
	global_load_dwordx4 v[10:13], v[2:3], off nt
	v_fma_f32 v89, -v92, v73, v89
	global_load_dwordx4 v[2:5], v[6:7], off nt
	ds_read2_b32 v[90:91], v69 offset1:65
	global_load_dwordx4 v[6:9], v[46:47], off nt
	v_lshl_add_u64 v[46:47], v[46:47], 0, s[26:27]
	s_ashr_i32 s26, s18, 30
	v_cmp_ge_f32_e64 s[18:19], |v89|, v73
	s_or_b32 s26, s26, 1
	s_and_b64 s[18:19], s[18:19], exec
	s_cselect_b32 s18, s26, 0
	v_readfirstlane_b32 s19, v94
	s_add_i32 s18, s19, s18
	s_sext_i32_i16 s19, s18
	s_mul_i32 s18, s18, s14
	s_sub_i32 s14, s34, s18
	s_sext_i32_i16 s14, s14
	s_lshl_b32 s28, s19, 6
	s_lshl_b32 s26, s14, 6
	s_ashr_i32 s29, s28, 31
	v_or_b32_e32 v73, s26, v67
	s_cmp_lg_u32 s15, 0
	global_load_dwordx4 v[46:49], v[46:47], off nt
	s_waitcnt lgkmcnt(0)
	v_cvt_pk_bf16_f32 v90, v90, v91
	ds_read2_b32 v[92:93], v69 offset0:130 offset1:195
	v_add_u32_e32 v89, 0x400, v69
	s_cselect_b64 s[18:19], -1, 0
	v_cmp_gt_i32_e32 vcc, s36, v73
	s_waitcnt lgkmcnt(0)
	v_cvt_pk_bf16_f32 v91, v92, v93
	ds_read2_b32 v[92:93], v89 offset0:4 offset1:69
	v_or_b32_e32 v98, s26, v74
	s_and_b64 vcc, s[18:19], vcc
	s_waitcnt lgkmcnt(0)
	v_cvt_pk_bf16_f32 v92, v92, v93
	ds_read2_b32 v[94:95], v89 offset0:134 offset1:199
	v_cndmask_b32_e32 v73, v73, v98, vcc
	s_waitcnt lgkmcnt(0)
	v_cvt_pk_bf16_f32 v93, v94, v95
	v_mul_hi_i32_i24_e32 v95, s6, v73
	v_mul_i32_i24_e32 v94, s6, v73
	v_lshl_add_u64 v[94:95], v[94:95], 1, s[4:5]
	s_lshl_b64 s[14:15], s[28:29], 1
	v_lshl_add_u64 v[94:95], v[94:95], 0, s[14:15]
	v_mov_b32_e32 v73, v71
	v_lshl_add_u64 v[94:95], v[94:95], 0, v[72:73]
	ds_read2_b32 v[96:97], v69 offset0:8 offset1:73
	global_store_dwordx4 v[94:95], v[90:93], off sc1
	s_mov_b32 s34, s37
	s_waitcnt lgkmcnt(0)
	v_cvt_pk_bf16_f32 v90, v96, v97
	ds_read2_b32 v[92:93], v69 offset0:138 offset1:203
	s_waitcnt lgkmcnt(0)
	v_cvt_pk_bf16_f32 v91, v92, v93
	ds_read2_b32 v[92:93], v89 offset0:12 offset1:77
	s_waitcnt lgkmcnt(0)
	v_cvt_pk_bf16_f32 v92, v92, v93
	ds_read2_b32 v[94:95], v89 offset0:142 offset1:207
	s_waitcnt lgkmcnt(0)
	v_cvt_pk_bf16_f32 v93, v94, v95
	v_or_b32_e32 v94, s26, v75
	v_cmp_gt_i32_e32 vcc, s36, v94
	v_or_b32_e32 v95, s26, v76
	s_and_b64 vcc, s[18:19], vcc
	v_cndmask_b32_e32 v94, v94, v95, vcc
	v_ashrrev_i32_e32 v95, 31, v94
	v_mul_lo_u32 v96, s6, v95
	v_mul_lo_u32 v97, s7, v94
	v_mad_u64_u32 v[94:95], s[28:29], s6, v94, 0
	v_add3_u32 v95, v95, v96, v97
	v_lshl_add_u64 v[94:95], v[94:95], 1, s[4:5]
	v_lshl_add_u64 v[94:95], v[94:95], 0, s[14:15]
	v_lshl_add_u64 v[94:95], v[94:95], 0, v[72:73]
	ds_read2_b32 v[96:97], v69 offset0:16 offset1:81
	global_store_dwordx4 v[94:95], v[90:93], off sc1
	s_waitcnt lgkmcnt(0)
	s_nop 0
	v_cvt_pk_bf16_f32 v90, v96, v97
	ds_read2_b32 v[92:93], v69 offset0:146 offset1:211
	s_waitcnt lgkmcnt(0)
	v_cvt_pk_bf16_f32 v91, v92, v93
	ds_read2_b32 v[92:93], v89 offset0:20 offset1:85
	s_waitcnt lgkmcnt(0)
	v_cvt_pk_bf16_f32 v92, v92, v93
	ds_read2_b32 v[94:95], v89 offset0:150 offset1:215
	s_waitcnt lgkmcnt(0)
; #define LAS __attribute__((address_space(3)))
; __device__ __forceinline__ unsigned pk2(float lo, float hi) { return pg8::cvt_pk_bf16(lo, hi); }
; __device__ __forceinline__ void tr_store(const TrD& d, LAS float* scr, int lane) {
;     const int nblk = d.N / 64, kb = d.item / nblk, nb = d.item % nblk, k0 = 64 * kb, n0 = 64 * nb, c = lane & 7;
; #pragma unroll
;     for (int j = 0; j < 8; ++j) { const int n = (lane >> 3) + 8 * j; const LAS float* s = scr + (8 * c) * 65 + n;
;         v4u o; o.x = pk2(s[0 * 65], s[1 * 65]); o.y = pk2(s[2 * 65], s[3 * 65]); o.z = pk2(s[4 * 65], s[5 * 65]); o.w = pk2(s[6 * 65], s[7 * 65]);
;         int dn = n0 + n; if (d.perm && dn < 1536) { const int f = dn & 127; dn = (dn & ~127) | ((f >> 6) * 64 + 2 * (f & 31) + ((f >> 5) & 1)); }
;         __builtin_nontemporal_store(o, (v4u*)(d.WT + (size_t)dn * d.K + k0 + 8 * c)); }
;     asm volatile("s_waitcnt lgkmcnt(0)" ::: "memory");
; }
	v_cvt_pk_bf16_f32 v93, v94, v95
	v_or_b32_e32 v94, s26, v77
	v_cmp_gt_i32_e32 vcc, s36, v94
	v_or_b32_e32 v95, s26, v78
	s_and_b64 vcc, s[18:19], vcc
	v_cndmask_b32_e32 v94, v94, v95, vcc
	v_ashrrev_i32_e32 v95, 31, v94
	v_mul_lo_u32 v96, s6, v95
	v_mul_lo_u32 v97, s7, v94
	v_mad_u64_u32 v[94:95], s[28:29], s6, v94, 0
	v_add3_u32 v95, v95, v96, v97
	v_lshl_add_u64 v[94:95], v[94:95], 1, s[4:5]
	v_lshl_add_u64 v[94:95], v[94:95], 0, s[14:15]
	v_lshl_add_u64 v[94:95], v[94:95], 0, v[72:73]
	ds_read2_b32 v[96:97], v69 offset0:24 offset1:89
	global_store_dwordx4 v[94:95], v[90:93], off sc1
	s_waitcnt lgkmcnt(0)
	s_nop 0
	v_cvt_pk_bf16_f32 v90, v96, v97
	ds_read2_b32 v[92:93], v69 offset0:154 offset1:219
	s_waitcnt lgkmcnt(0)
	v_cvt_pk_bf16_f32 v91, v92, v93
	ds_read2_b32 v[92:93], v89 offset0:28 offset1:93
	s_waitcnt lgkmcnt(0)
	v_cvt_pk_bf16_f32 v92, v92, v93
	ds_read2_b32 v[94:95], v89 offset0:158 offset1:223
	s_waitcnt lgkmcnt(0)
	v_cvt_pk_bf16_f32 v93, v94, v95
	v_or_b32_e32 v94, s26, v79
	v_cmp_gt_i32_e32 vcc, s36, v94
	v_or_b32_e32 v95, s26, v80
	s_and_b64 vcc, s[18:19], vcc
	v_cndmask_b32_e32 v94, v94, v95, vcc
	v_ashrrev_i32_e32 v95, 31, v94
	v_mul_lo_u32 v96, s6, v95
	v_mul_lo_u32 v97, s7, v94
	v_mad_u64_u32 v[94:95], s[28:29], s6, v94, 0
	v_add3_u32 v95, v95, v96, v97
	v_lshl_add_u64 v[94:95], v[94:95], 1, s[4:5]
	v_lshl_add_u64 v[94:95], v[94:95], 0, s[14:15]
	v_lshl_add_u64 v[94:95], v[94:95], 0, v[72:73]
	ds_read2_b32 v[96:97], v69 offset0:32 offset1:97
	global_store_dwordx4 v[94:95], v[90:93], off sc1
	s_waitcnt lgkmcnt(0)
	s_nop 0
	v_cvt_pk_bf16_f32 v90, v96, v97
	ds_read2_b32 v[92:93], v69 offset0:162 offset1:227
	s_waitcnt lgkmcnt(0)
	v_cvt_pk_bf16_f32 v91, v92, v93
	ds_read2_b32 v[92:93], v89 offset0:36 offset1:101
	s_waitcnt lgkmcnt(0)
	v_cvt_pk_bf16_f32 v92, v92, v93
	ds_read2_b32 v[94:95], v89 offset0:166 offset1:231
	s_waitcnt lgkmcnt(0)
	v_cvt_pk_bf16_f32 v93, v94, v95
	v_or_b32_e32 v94, s26, v81
	v_cmp_gt_i32_e32 vcc, s36, v94
	v_or_b32_e32 v95, 1, v98
	s_and_b64 vcc, s[18:19], vcc
	v_cndmask_b32_e32 v94, v94, v95, vcc
	v_ashrrev_i32_e32 v95, 31, v94
	v_mul_lo_u32 v96, s6, v95
	v_mul_lo_u32 v97, s7, v94
	v_mad_u64_u32 v[94:95], s[28:29], s6, v94, 0
	v_add3_u32 v95, v95, v96, v97
	v_lshl_add_u64 v[94:95], v[94:95], 1, s[4:5]
	v_lshl_add_u64 v[94:95], v[94:95], 0, s[14:15]
	v_lshl_add_u64 v[94:95], v[94:95], 0, v[72:73]
	ds_read2_b32 v[96:97], v69 offset0:40 offset1:105
	global_store_dwordx4 v[94:95], v[90:93], off sc1
	s_waitcnt lgkmcnt(0)
	s_nop 0
	v_cvt_pk_bf16_f32 v90, v96, v97
	ds_read2_b32 v[92:93], v69 offset0:170 offset1:235
	s_waitcnt lgkmcnt(0)
	v_cvt_pk_bf16_f32 v91, v92, v93
	ds_read2_b32 v[92:93], v89 offset0:44 offset1:109
	s_waitcnt lgkmcnt(0)
	v_cvt_pk_bf16_f32 v92, v92, v93
	ds_read2_b32 v[94:95], v89 offset0:174 offset1:239
	s_waitcnt lgkmcnt(0)
	v_cvt_pk_bf16_f32 v93, v94, v95
	v_or_b32_e32 v94, s26, v82
	v_cmp_gt_i32_e32 vcc, s36, v94
	v_or_b32_e32 v95, s26, v83
	s_and_b64 vcc, s[18:19], vcc
	v_cndmask_b32_e32 v94, v94, v95, vcc
	v_mul_hi_i32_i24_e32 v95, s6, v94
	v_mul_i32_i24_e32 v94, s6, v94
	v_lshl_add_u64 v[94:95], v[94:95], 1, s[4:5]
	v_lshl_add_u64 v[94:95], v[94:95], 0, s[14:15]
	v_lshl_add_u64 v[94:95], v[94:95], 0, v[72:73]
	ds_read2_b32 v[96:97], v69 offset0:48 offset1:113
	global_store_dwordx4 v[94:95], v[90:93], off sc1
	s_waitcnt lgkmcnt(0)
	s_nop 0
	v_cvt_pk_bf16_f32 v90, v96, v97
	ds_read2_b32 v[92:93], v69 offset0:178 offset1:243
	s_waitcnt lgkmcnt(0)
	v_cvt_pk_bf16_f32 v91, v92, v93
	ds_read2_b32 v[92:93], v89 offset0:52 offset1:117
	s_waitcnt lgkmcnt(0)
	v_cvt_pk_bf16_f32 v92, v92, v93
	ds_read2_b32 v[94:95], v89 offset0:182 offset1:247
	s_waitcnt lgkmcnt(0)
	v_cvt_pk_bf16_f32 v93, v94, v95
	v_or_b32_e32 v94, s26, v84
	v_cmp_gt_i32_e32 vcc, s36, v94
	v_or_b32_e32 v95, s26, v85
	s_and_b64 vcc, s[18:19], vcc
	v_cndmask_b32_e32 v94, v94, v95, vcc
	v_mul_hi_i32_i24_e32 v95, s6, v94
	v_mul_i32_i24_e32 v94, s6, v94
	v_lshl_add_u64 v[94:95], v[94:95], 1, s[4:5]
	v_lshl_add_u64 v[94:95], v[94:95], 0, s[14:15]
	v_lshl_add_u64 v[94:95], v[94:95], 0, v[72:73]
	ds_read2_b32 v[96:97], v69 offset0:56 offset1:121
	global_store_dwordx4 v[94:95], v[90:93], off sc1
	s_waitcnt lgkmcnt(0)
	s_nop 0
	v_cvt_pk_bf16_f32 v90, v96, v97
	ds_read2_b32 v[92:93], v69 offset0:186 offset1:251
	s_waitcnt lgkmcnt(0)
	v_cvt_pk_bf16_f32 v91, v92, v93
	ds_read2_b32 v[92:93], v89 offset0:60 offset1:125
	s_waitcnt lgkmcnt(0)
	v_cvt_pk_bf16_f32 v92, v92, v93
	ds_read2_b32 v[94:95], v89 offset0:190 offset1:255
	v_or_b32_e32 v89, s26, v86
	v_cmp_gt_i32_e32 vcc, s36, v89
	s_waitcnt lgkmcnt(0)
	v_cvt_pk_bf16_f32 v93, v94, v95
	v_or_b32_e32 v94, s26, v88
	s_and_b64 vcc, s[18:19], vcc
	v_cndmask_b32_e32 v89, v89, v94, vcc
	v_mul_hi_i32_i24_e32 v95, s6, v89
	v_mul_i32_i24_e32 v94, s6, v89
	v_lshl_add_u64 v[94:95], v[94:95], 1, s[4:5]
	v_lshl_add_u64 v[94:95], v[94:95], 0, s[14:15]
	v_lshl_add_u64 v[94:95], v[94:95], 0, v[72:73]
	global_store_dwordx4 v[94:95], v[90:93], off sc1
	s_waitcnt lgkmcnt(0)
	s_andn2_b64 vcc, exec, s[20:21]
	s_mov_b32 s15, s38
	s_mov_b32 s18, s12
	s_mov_b64 s[6:7], s[24:25]
	s_mov_b64 s[4:5], s[22:23]
	s_cbranch_vccz .LBB0_80

; #define LAS __attribute__((address_space(3)))
; __device__ __forceinline__ unsigned pk2(float lo, float hi) { return pg8::cvt_pk_bf16(lo, hi); }
; __device__ __forceinline__ void tr_load(const TrD& d, int lane, f32x4 (&v)[16]) {
;     const int nblk = d.N / 64, kb = d.item / nblk, nb = d.item % nblk, k0 = 64 * kb, n0 = 64 * nb, lr = lane >> 4, lc = (lane & 15) * 4;
;     const float* src = d.W + (size_t)(k0 + lr) * d.N + n0 + lc;
; #pragma unroll
;     for (int i = 0; i < 16; ++i) v[i] = __builtin_nontemporal_load((const f32x4*)(src + (size_t)(4 * i) * d.N));
; }
; __device__ __forceinline__ void tr_lds_write(LAS float* scr, int lane, const f32x4 (&v)[16]) {
;     const int lr = lane >> 4, lc = (lane & 15) * 4;
; #pragma unroll
;     for (int i = 0; i < 16; ++i) { const int kk = 4 * i + lr; scr[kk * 65 + lc + 0] = v[i][0]; scr[kk * 65 + lc + 1] = v[i][1]; scr[kk * 65 + lc + 2] = v[i][2]; scr[kk * 65 + lc + 3] = v[i][3]; }
;     asm volatile("s_waitcnt lgkmcnt(0)" ::: "memory");
; }
; __device__ __forceinline__ void tr_store(const TrD& d, LAS float* scr, int lane) {
;     const int nblk = d.N / 64, kb = d.item / nblk, nb = d.item % nblk, k0 = 64 * kb, n0 = 64 * nb, c = lane & 7;
; #pragma unroll
;     for (int j = 0; j < 8; ++j) { const int n = (lane >> 3) + 8 * j; const LAS float* s = scr + (8 * c) * 65 + n;
;         v4u o; o.x = pk2(s[0 * 65], s[1 * 65]); o.y = pk2(s[2 * 65], s[3 * 65]); o.z = pk2(s[4 * 65], s[5 * 65]); o.w = pk2(s[6 * 65], s[7 * 65]);
;         int dn = n0 + n; if (d.perm && dn < 1536) { const int f = dn & 127; dn = (dn & ~127) | ((f >> 6) * 64 + 2 * (f & 31) + ((f >> 5) & 1)); }
;         __builtin_nontemporal_store(o, (v4u*)(d.WT + (size_t)dn * d.K + k0 + 8 * c)); }
.LBB0_821:
	s_lshr_b32 s16, s8, 6
	v_cvt_f32_i32_e32 v1, s16
	s_sext_i32_i16 s30, s49
	v_cvt_f32_i32_e32 v0, s30
	s_ashr_i32 s39, s30, 30
	v_rcp_iflag_f32_e32 v2, v1
	s_or_b32 s39, s39, 1
	v_mul_f32_e32 v2, v0, v2
	v_trunc_f32_e32 v2, v2
	v_fma_f32 v0, -v2, v1, v0
	v_cvt_i32_f32_e32 v2, v2
	v_cmp_ge_f32_e64 s[42:43], |v0|, v1
	s_and_b64 s[42:43], s[42:43], exec
	s_cselect_b32 s30, s39, 0
	v_readfirstlane_b32 s39, v2
	s_add_i32 s30, s39, s30
	s_sext_i32_i16 s39, s30
	s_mul_i32 s30, s30, s16
	s_sub_i32 s16, s49, s30
	s_sext_i32_i16 s16, s16
	v_lshl_or_b32 v0, s39, 6, v66
	s_lshl_b32 s42, s16, 6
	v_mul_hi_i32_i24_e32 v1, s8, v0
	v_mul_i32_i24_e32 v0, s8, v0
	s_waitcnt lgkmcnt(0)
	v_lshl_add_u64 v[0:1], v[0:1], 2, s[40:41]
	s_ashr_i32 s43, s42, 31
	v_lshl_add_u64 v[0:1], s[42:43], 2, v[0:1]
	v_lshl_add_u64 v[0:1], v[0:1], 0, v[212:213]
	s_lshl_b64 s[40:41], s[8:9], 4
	global_load_dwordx4 v[52:55], v[0:1], off nt
	v_lshl_add_u64 v[0:1], v[0:1], 0, s[40:41]
	global_load_dwordx4 v[60:63], v[0:1], off nt
	v_lshl_add_u64 v[0:1], v[0:1], 0, s[40:41]
	s_lshr_b32 s16, s38, 6
	global_load_dwordx4 v[48:51], v[0:1], off nt
	v_lshl_add_u64 v[0:1], v[0:1], 0, s[40:41]
	v_cvt_f32_i32_e32 v84, s16
	global_load_dwordx4 v[56:59], v[0:1], off nt
	v_lshl_add_u64 v[0:1], v[0:1], 0, s[40:41]
	global_load_dwordx4 v[40:43], v[0:1], off nt
	v_lshl_add_u64 v[0:1], v[0:1], 0, s[40:41]
	global_load_dwordx4 v[44:47], v[0:1], off nt
	v_lshl_add_u64 v[0:1], v[0:1], 0, s[40:41]
	s_sext_i32_i16 s30, s48
	global_load_dwordx4 v[32:35], v[0:1], off nt
	v_lshl_add_u64 v[0:1], v[0:1], 0, s[40:41]
	v_cvt_f32_i32_e32 v65, s30
	v_rcp_iflag_f32_e32 v85, v84
	global_load_dwordx4 v[36:39], v[0:1], off nt
	v_lshl_add_u64 v[0:1], v[0:1], 0, s[40:41]
	global_load_dwordx4 v[24:27], v[0:1], off nt
	v_lshl_add_u64 v[0:1], v[0:1], 0, s[40:41]
	global_load_dwordx4 v[20:23], v[0:1], off nt
	v_lshl_add_u64 v[0:1], v[0:1], 0, s[40:41]
	global_load_dwordx4 v[16:19], v[0:1], off nt
	v_lshl_add_u64 v[0:1], v[0:1], 0, s[40:41]
	v_mul_f32_e32 v85, v65, v85
	global_load_dwordx4 v[12:15], v[0:1], off nt
	v_lshl_add_u64 v[0:1], v[0:1], 0, s[40:41]
	v_trunc_f32_e32 v85, v85
	global_load_dwordx4 v[8:11], v[0:1], off nt
	v_lshl_add_u64 v[0:1], v[0:1], 0, s[40:41]
	v_fma_f32 v65, -v85, v84, v65
	v_cvt_i32_f32_e32 v85, v85
	v_lshl_add_u64 v[28:29], v[0:1], 0, s[40:41]
	s_ashr_i32 s38, s30, 30
	global_load_dwordx4 v[4:7], v[0:1], off nt
	s_nop 0
	global_load_dwordx4 v[0:3], v[28:29], off nt
	v_lshl_add_u64 v[28:29], v[28:29], 0, s[40:41]
	s_or_b32 s40, s38, 1
	v_cmp_ge_f32_e64 s[38:39], |v65|, v84
	s_and_b64 s[38:39], s[38:39], exec
	s_cselect_b32 s30, s40, 0
	v_readfirstlane_b32 s38, v85
	s_add_i32 s30, s38, s30
	s_sext_i32_i16 s38, s30
	s_mul_i32 s30, s30, s16
	s_sub_i32 s16, s48, s30
	s_sext_i32_i16 s16, s16
	s_lshl_b32 s38, s38, 6
	s_lshl_b32 s42, s16, 6
	s_ashr_i32 s39, s38, 31
	ds_read2_b32 v[84:85], v68 offset1:65
	global_load_dwordx4 v[28:31], v[28:29], off nt
	s_waitcnt lgkmcnt(0)
	v_cvt_pk_bf16_f32 v86, v84, v85
	ds_read2_b32 v[84:85], v68 offset0:130 offset1:195
	v_or_b32_e32 v65, s42, v67
	s_cmp_lg_u32 s47, 0
	s_movk_i32 s16, 0x600
	s_waitcnt lgkmcnt(0)
	v_cvt_pk_bf16_f32 v87, v84, v85
	v_add_u32_e32 v84, 0x400, v68
	s_cselect_b64 s[40:41], -1, 0
	v_cmp_gt_i32_e32 vcc, s16, v65
	ds_read2_b32 v[88:89], v84 offset0:4 offset1:69
	s_and_b64 vcc, s[40:41], vcc
	v_or_b32_e32 v85, s42, v69
	s_waitcnt lgkmcnt(0)
	v_cvt_pk_bf16_f32 v88, v88, v89
	ds_read2_b32 v[90:91], v84 offset0:134 offset1:199
	v_cndmask_b32_e32 v65, v65, v85, vcc
	s_waitcnt lgkmcnt(0)
	v_cvt_pk_bf16_f32 v89, v90, v91
	v_mul_hi_i32_i24_e32 v91, s6, v65
	v_mul_i32_i24_e32 v90, s6, v65
	v_lshl_add_u64 v[90:91], v[90:91], 1, s[2:3]
	s_lshl_b64 s[38:39], s[38:39], 1
	v_lshl_add_u64 v[90:91], v[90:91], 0, s[38:39]
	v_mov_b32_e32 v65, v213
	v_lshl_add_u64 v[90:91], v[90:91], 0, v[64:65]
	global_store_dwordx4 v[90:91], v[86:89], off sc1
	ds_read2_b32 v[86:87], v68 offset0:8 offset1:73
	v_or_b32_e32 v85, 1, v85
	s_waitcnt lgkmcnt(0)
	v_cvt_pk_bf16_f32 v86, v86, v87
	ds_read2_b32 v[88:89], v68 offset0:138 offset1:203
	s_waitcnt lgkmcnt(0)
	v_cvt_pk_bf16_f32 v87, v88, v89
	ds_read2_b32 v[88:89], v84 offset0:12 offset1:77
	s_waitcnt lgkmcnt(0)
	v_cvt_pk_bf16_f32 v88, v88, v89
	ds_read2_b32 v[90:91], v84 offset0:142 offset1:207
	s_waitcnt lgkmcnt(0)
	v_cvt_pk_bf16_f32 v89, v90, v91
	v_or_b32_e32 v90, s42, v70
	v_cmp_gt_i32_e32 vcc, s16, v90
	s_and_b64 vcc, s[40:41], vcc
	v_or_b32_e32 v91, s42, v71
	v_cndmask_b32_e32 v90, v90, v91, vcc
	v_ashrrev_i32_e32 v91, 31, v90
	v_mul_lo_u32 v92, s6, v91
	v_mul_lo_u32 v93, s7, v90
	v_mad_u64_u32 v[90:91], s[52:53], s6, v90, 0
	v_add3_u32 v91, v91, v92, v93
	v_lshl_add_u64 v[90:91], v[90:91], 1, s[2:3]
	v_lshl_add_u64 v[90:91], v[90:91], 0, s[38:39]
	v_lshl_add_u64 v[90:91], v[90:91], 0, v[64:65]
	global_store_dwordx4 v[90:91], v[86:89], off sc1
	ds_read2_b32 v[86:87], v68 offset0:16 offset1:81
	s_add_i32 s45, s45, s5
	s_waitcnt lgkmcnt(0)
	v_cvt_pk_bf16_f32 v86, v86, v87
	ds_read2_b32 v[88:89], v68 offset0:146 offset1:211
	s_waitcnt lgkmcnt(0)
	v_cvt_pk_bf16_f32 v87, v88, v89
	ds_read2_b32 v[88:89], v84 offset0:20 offset1:85
	s_waitcnt lgkmcnt(0)
; #define LAS __attribute__((address_space(3)))
; __device__ __forceinline__ unsigned pk2(float lo, float hi) { return pg8::cvt_pk_bf16(lo, hi); }
; __device__ __forceinline__ void tr_store(const TrD& d, LAS float* scr, int lane) {
;     const int nblk = d.N / 64, kb = d.item / nblk, nb = d.item % nblk, k0 = 64 * kb, n0 = 64 * nb, c = lane & 7;
; #pragma unroll
;     for (int j = 0; j < 8; ++j) { const int n = (lane >> 3) + 8 * j; const LAS float* s = scr + (8 * c) * 65 + n;
;         v4u o; o.x = pk2(s[0 * 65], s[1 * 65]); o.y = pk2(s[2 * 65], s[3 * 65]); o.z = pk2(s[4 * 65], s[5 * 65]); o.w = pk2(s[6 * 65], s[7 * 65]);
;         int dn = n0 + n; if (d.perm && dn < 1536) { const int f = dn & 127; dn = (dn & ~127) | ((f >> 6) * 64 + 2 * (f & 31) + ((f >> 5) & 1)); }
;         __builtin_nontemporal_store(o, (v4u*)(d.WT + (size_t)dn * d.K + k0 + 8 * c)); }
;     asm volatile("s_waitcnt lgkmcnt(0)" ::: "memory");
; }
	v_cvt_pk_bf16_f32 v88, v88, v89
	ds_read2_b32 v[90:91], v84 offset0:150 offset1:215
	s_waitcnt lgkmcnt(0)
	v_cvt_pk_bf16_f32 v89, v90, v91
	v_or_b32_e32 v90, s42, v72
	v_cmp_gt_i32_e32 vcc, s16, v90
	s_and_b64 vcc, s[40:41], vcc
	v_or_b32_e32 v91, s42, v73
	v_cndmask_b32_e32 v90, v90, v91, vcc
	v_ashrrev_i32_e32 v91, 31, v90
	v_mul_lo_u32 v92, s6, v91
	v_mul_lo_u32 v93, s7, v90
	v_mad_u64_u32 v[90:91], s[52:53], s6, v90, 0
	v_add3_u32 v91, v91, v92, v93
	v_lshl_add_u64 v[90:91], v[90:91], 1, s[2:3]
	v_lshl_add_u64 v[90:91], v[90:91], 0, s[38:39]
	v_lshl_add_u64 v[90:91], v[90:91], 0, v[64:65]
	global_store_dwordx4 v[90:91], v[86:89], off sc1
	ds_read2_b32 v[86:87], v68 offset0:24 offset1:89
	s_mov_b32 s47, s50
	s_waitcnt lgkmcnt(0)
	v_cvt_pk_bf16_f32 v86, v86, v87
	ds_read2_b32 v[88:89], v68 offset0:154 offset1:219
	s_waitcnt lgkmcnt(0)
	v_cvt_pk_bf16_f32 v87, v88, v89
	ds_read2_b32 v[88:89], v84 offset0:28 offset1:93
	s_waitcnt lgkmcnt(0)
	v_cvt_pk_bf16_f32 v88, v88, v89
	ds_read2_b32 v[90:91], v84 offset0:158 offset1:223
	s_waitcnt lgkmcnt(0)
	v_cvt_pk_bf16_f32 v89, v90, v91
	v_or_b32_e32 v90, s42, v74
	v_cmp_gt_i32_e32 vcc, s16, v90
	s_and_b64 vcc, s[40:41], vcc
	v_or_b32_e32 v91, s42, v75
	v_cndmask_b32_e32 v90, v90, v91, vcc
	v_ashrrev_i32_e32 v91, 31, v90
	v_mul_lo_u32 v92, s6, v91
	v_mul_lo_u32 v93, s7, v90
	v_mad_u64_u32 v[90:91], s[52:53], s6, v90, 0
	v_add3_u32 v91, v91, v92, v93
	v_lshl_add_u64 v[90:91], v[90:91], 1, s[2:3]
	v_lshl_add_u64 v[90:91], v[90:91], 0, s[38:39]
	v_lshl_add_u64 v[90:91], v[90:91], 0, v[64:65]
	global_store_dwordx4 v[90:91], v[86:89], off sc1
	ds_read2_b32 v[86:87], v68 offset0:32 offset1:97
	s_mov_b32 s48, s49
	s_waitcnt lgkmcnt(0)
	v_cvt_pk_bf16_f32 v86, v86, v87
	ds_read2_b32 v[88:89], v68 offset0:162 offset1:227
	s_waitcnt lgkmcnt(0)
	v_cvt_pk_bf16_f32 v87, v88, v89
	ds_read2_b32 v[88:89], v84 offset0:36 offset1:101
	s_waitcnt lgkmcnt(0)
	v_cvt_pk_bf16_f32 v88, v88, v89
	ds_read2_b32 v[90:91], v84 offset0:166 offset1:231
	s_waitcnt lgkmcnt(0)
	v_cvt_pk_bf16_f32 v89, v90, v91
	v_or_b32_e32 v90, s42, v76
	v_cmp_gt_i32_e32 vcc, s16, v90
	s_and_b64 vcc, s[40:41], vcc
	s_nop 0
	v_cndmask_b32_e32 v85, v90, v85, vcc
	v_ashrrev_i32_e32 v90, 31, v85
	v_mul_lo_u32 v92, s6, v90
	v_mul_lo_u32 v93, s7, v85
	v_mad_u64_u32 v[90:91], s[52:53], s6, v85, 0
	v_add3_u32 v91, v91, v92, v93
	v_lshl_add_u64 v[90:91], v[90:91], 1, s[2:3]
	v_lshl_add_u64 v[90:91], v[90:91], 0, s[38:39]
	v_lshl_add_u64 v[90:91], v[90:91], 0, v[64:65]
	global_store_dwordx4 v[90:91], v[86:89], off sc1
	ds_read2_b32 v[86:87], v68 offset0:40 offset1:105
	v_or_b32_e32 v85, s42, v77
	s_waitcnt lgkmcnt(0)
	v_cvt_pk_bf16_f32 v86, v86, v87
	ds_read2_b32 v[88:89], v68 offset0:170 offset1:235
	s_waitcnt lgkmcnt(0)
	v_cvt_pk_bf16_f32 v87, v88, v89
	ds_read2_b32 v[88:89], v84 offset0:44 offset1:109
	s_waitcnt lgkmcnt(0)
	v_cvt_pk_bf16_f32 v88, v88, v89
	ds_read2_b32 v[90:91], v84 offset0:174 offset1:239
	v_cmp_gt_i32_e32 vcc, s16, v85
	s_waitcnt lgkmcnt(0)
	v_cvt_pk_bf16_f32 v89, v90, v91
	s_and_b64 vcc, s[40:41], vcc
	v_or_b32_e32 v90, s42, v78
	v_cndmask_b32_e32 v85, v85, v90, vcc
	v_mul_hi_i32_i24_e32 v91, s6, v85
	v_mul_i32_i24_e32 v90, s6, v85
	v_lshl_add_u64 v[90:91], v[90:91], 1, s[2:3]
	v_lshl_add_u64 v[90:91], v[90:91], 0, s[38:39]
	v_lshl_add_u64 v[90:91], v[90:91], 0, v[64:65]
	global_store_dwordx4 v[90:91], v[86:89], off sc1
	ds_read2_b32 v[86:87], v68 offset0:48 offset1:113
	v_or_b32_e32 v85, s42, v79
	s_waitcnt lgkmcnt(0)
	v_cvt_pk_bf16_f32 v86, v86, v87
	ds_read2_b32 v[88:89], v68 offset0:178 offset1:243
	s_waitcnt lgkmcnt(0)
	v_cvt_pk_bf16_f32 v87, v88, v89
	ds_read2_b32 v[88:89], v84 offset0:52 offset1:117
	s_waitcnt lgkmcnt(0)
	v_cvt_pk_bf16_f32 v88, v88, v89
	ds_read2_b32 v[90:91], v84 offset0:182 offset1:247
	v_cmp_gt_i32_e32 vcc, s16, v85
	s_waitcnt lgkmcnt(0)
	v_cvt_pk_bf16_f32 v89, v90, v91
	s_and_b64 vcc, s[40:41], vcc
	v_or_b32_e32 v90, s42, v80
	v_cndmask_b32_e32 v85, v85, v90, vcc
	v_mul_hi_i32_i24_e32 v91, s6, v85
	v_mul_i32_i24_e32 v90, s6, v85
	v_lshl_add_u64 v[90:91], v[90:91], 1, s[2:3]
	v_lshl_add_u64 v[90:91], v[90:91], 0, s[38:39]
	v_lshl_add_u64 v[90:91], v[90:91], 0, v[64:65]
	global_store_dwordx4 v[90:91], v[86:89], off sc1
	ds_read2_b32 v[86:87], v68 offset0:56 offset1:121
	s_waitcnt lgkmcnt(0)
	v_cvt_pk_bf16_f32 v86, v86, v87
	ds_read2_b32 v[88:89], v68 offset0:186 offset1:251
	s_waitcnt lgkmcnt(0)
	v_cvt_pk_bf16_f32 v87, v88, v89
	ds_read2_b32 v[88:89], v84 offset0:60 offset1:125
	s_waitcnt lgkmcnt(0)
	v_cvt_pk_bf16_f32 v88, v88, v89
	ds_read2_b32 v[84:85], v84 offset0:190 offset1:255
	s_waitcnt lgkmcnt(0)
	v_cvt_pk_bf16_f32 v89, v84, v85
	v_or_b32_e32 v84, s42, v81
	v_cmp_gt_i32_e32 vcc, s16, v84
	s_and_b64 vcc, s[40:41], vcc
	v_or_b32_e32 v85, s42, v82
	v_cndmask_b32_e32 v84, v84, v85, vcc
	v_mul_hi_i32_i24_e32 v85, s6, v84
	v_mul_i32_i24_e32 v84, s6, v84
	v_lshl_add_u64 v[84:85], v[84:85], 1, s[2:3]
	v_lshl_add_u64 v[84:85], v[84:85], 0, s[38:39]
	v_lshl_add_u64 v[84:85], v[84:85], 0, v[64:65]
	global_store_dwordx4 v[84:85], v[86:89], off sc1
	s_waitcnt lgkmcnt(0)
	s_add_i32 s2, s44, s45
	s_cmpk_gt_i32 s2, 0x3ff
	s_mov_b32 s38, s8
	s_mov_b64 s[6:7], s[36:37]
	s_mov_b64 s[2:3], s[34:35]
	s_cbranch_scc1 .LBB0_846

; #define LAS __attribute__((address_space(3)))
; __device__ __forceinline__ unsigned pk2(float lo, float hi) { return pg8::cvt_pk_bf16(lo, hi); }
; __device__ __forceinline__ void tr_load(const TrD& d, int lane, f32x4 (&v)[16]) {
;     const int nblk = d.N / 64, kb = d.item / nblk, nb = d.item % nblk, k0 = 64 * kb, n0 = 64 * nb, lr = lane >> 4, lc = (lane & 15) * 4;
;     const float* src = d.W + (size_t)(k0 + lr) * d.N + n0 + lc;
; #pragma unroll
;     for (int i = 0; i < 16; ++i) v[i] = __builtin_nontemporal_load((const f32x4*)(src + (size_t)(4 * i) * d.N));
; }
; __device__ __forceinline__ void tr_lds_write(LAS float* scr, int lane, const f32x4 (&v)[16]) {
;     const int lr = lane >> 4, lc = (lane & 15) * 4;
; #pragma unroll
;     for (int i = 0; i < 16; ++i) { const int kk = 4 * i + lr; scr[kk * 65 + lc + 0] = v[i][0]; scr[kk * 65 + lc + 1] = v[i][1]; scr[kk * 65 + lc + 2] = v[i][2]; scr[kk * 65 + lc + 3] = v[i][3]; }
;     asm volatile("s_waitcnt lgkmcnt(0)" ::: "memory");
; }
; __device__ __forceinline__ void tr_store(const TrD& d, LAS float* scr, int lane) {
;     const int nblk = d.N / 64, kb = d.item / nblk, nb = d.item % nblk, k0 = 64 * kb, n0 = 64 * nb, c = lane & 7;
; #pragma unroll
;     for (int j = 0; j < 8; ++j) { const int n = (lane >> 3) + 8 * j; const LAS float* s = scr + (8 * c) * 65 + n;
;         v4u o; o.x = pk2(s[0 * 65], s[1 * 65]); o.y = pk2(s[2 * 65], s[3 * 65]); o.z = pk2(s[4 * 65], s[5 * 65]); o.w = pk2(s[6 * 65], s[7 * 65]);
;         int dn = n0 + n; if (d.perm && dn < 1536) { const int f = dn & 127; dn = (dn & ~127) | ((f >> 6) * 64 + 2 * (f & 31) + ((f >> 5) & 1)); }
;         __builtin_nontemporal_store(o, (v4u*)(d.WT + (size_t)dn * d.K + k0 + 8 * c)); }
.LBB0_1514:
	s_lshr_b32 s2, s8, 6
	v_cvt_f32_i32_e32 v1, s2
	s_sext_i32_i16 s3, s50
	v_cvt_f32_i32_e32 v0, s3
	s_ashr_i32 s16, s3, 30
	v_rcp_iflag_f32_e32 v2, v1
	s_or_b32 s16, s16, 1
	ds_read2_b32 v[86:87], v69 offset1:65
	v_add_u32_e32 v85, 0x400, v69
	v_mul_f32_e32 v2, v0, v2
	v_trunc_f32_e32 v2, v2
	v_fma_f32 v0, -v2, v1, v0
	v_cvt_i32_f32_e32 v2, v2
	v_cmp_ge_f32_e64 s[44:45], |v0|, v1
	s_and_b64 s[44:45], s[44:45], exec
	s_cselect_b32 s3, s16, 0
	v_readfirstlane_b32 s16, v2
	s_add_i32 s3, s16, s3
	s_sext_i32_i16 s16, s3
	s_mul_i32 s3, s3, s2
	s_sub_i32 s2, s50, s3
	s_sext_i32_i16 s2, s2
	s_lshl_b32 s44, s2, 6
	s_lshr_b32 s2, s40, 6
	v_cvt_f32_u32_e32 v65, s2
	v_lshl_or_b32 v0, s16, 6, v67
	v_mul_hi_i32_i24_e32 v1, s8, v0
	v_mul_i32_i24_e32 v0, s8, v0
	v_rcp_iflag_f32_e32 v65, v65
	s_sub_i32 s30, 0, s2
	s_waitcnt lgkmcnt(0)
	v_lshl_add_u64 v[0:1], v[0:1], 2, s[42:43]
	s_ashr_i32 s45, s44, 31
	v_mul_f32_e32 v65, 0x4f7ffffe, v65
	v_cvt_u32_f32_e32 v65, v65
	v_lshl_add_u64 v[0:1], s[44:45], 2, v[0:1]
	v_lshl_add_u64 v[0:1], v[0:1], 0, v[212:213]
	s_lshl_b64 s[42:43], s[8:9], 4
	v_readfirstlane_b32 s40, v65
	s_mul_i32 s30, s30, s40
	s_mul_hi_u32 s30, s40, s30
	s_abs_i32 s16, s51
	s_add_i32 s40, s40, s30
	global_load_dwordx4 v[52:55], v[0:1], off nt
	v_lshl_add_u64 v[0:1], v[0:1], 0, s[42:43]
	s_mul_hi_u32 s30, s16, s40
	global_load_dwordx4 v[60:63], v[0:1], off nt
	v_lshl_add_u64 v[0:1], v[0:1], 0, s[42:43]
	s_mul_i32 s40, s30, s2
	global_load_dwordx4 v[48:51], v[0:1], off nt
	v_lshl_add_u64 v[0:1], v[0:1], 0, s[42:43]
	s_sub_i32 s16, s16, s40
	global_load_dwordx4 v[56:59], v[0:1], off nt
	v_lshl_add_u64 v[0:1], v[0:1], 0, s[42:43]
	s_ashr_i32 s3, s51, 31
	s_add_i32 s40, s30, 1
	s_sub_i32 s41, s16, s2
	global_load_dwordx4 v[40:43], v[0:1], off nt
	v_lshl_add_u64 v[0:1], v[0:1], 0, s[42:43]
	s_cmp_ge_u32 s16, s2
	global_load_dwordx4 v[44:47], v[0:1], off nt
	v_lshl_add_u64 v[0:1], v[0:1], 0, s[42:43]
	s_cselect_b32 s30, s40, s30
	global_load_dwordx4 v[32:35], v[0:1], off nt
	v_lshl_add_u64 v[0:1], v[0:1], 0, s[42:43]
	s_cselect_b32 s16, s41, s16
	s_add_i32 s40, s30, 1
	global_load_dwordx4 v[36:39], v[0:1], off nt
	v_lshl_add_u64 v[0:1], v[0:1], 0, s[42:43]
	s_cmp_ge_u32 s16, s2
	global_load_dwordx4 v[24:27], v[0:1], off nt
	v_lshl_add_u64 v[0:1], v[0:1], 0, s[42:43]
	s_cselect_b32 s16, s40, s30
	global_load_dwordx4 v[20:23], v[0:1], off nt
	v_lshl_add_u64 v[0:1], v[0:1], 0, s[42:43]
	s_xor_b32 s16, s16, s3
	global_load_dwordx4 v[16:19], v[0:1], off nt
	v_lshl_add_u64 v[0:1], v[0:1], 0, s[42:43]
	s_sub_i32 s3, s16, s3
	global_load_dwordx4 v[12:15], v[0:1], off nt
	v_lshl_add_u64 v[0:1], v[0:1], 0, s[42:43]
	s_mul_i32 s2, s3, s2
	global_load_dwordx4 v[8:11], v[0:1], off nt
	v_lshl_add_u64 v[0:1], v[0:1], 0, s[42:43]
	s_sub_i32 s2, s51, s2
	s_lshl_b32 s40, s3, 6
	v_lshl_add_u64 v[28:29], v[0:1], 0, s[42:43]
	s_lshl_b32 s44, s2, 6
	s_ashr_i32 s41, s40, 31
	global_load_dwordx4 v[4:7], v[0:1], off nt
	v_or_b32_e32 v65, s44, v68
	global_load_dwordx4 v[0:3], v[28:29], off nt
	v_lshl_add_u64 v[28:29], v[28:29], 0, s[42:43]
	s_cmp_lg_u32 s49, 0
	s_movk_i32 s2, 0x600
	global_load_dwordx4 v[28:31], v[28:29], off nt
	v_cvt_pk_bf16_f32 v86, v86, v87
	ds_read2_b32 v[88:89], v69 offset0:130 offset1:195
	s_cselect_b64 s[42:43], -1, 0
	v_cmp_gt_i32_e32 vcc, s2, v65
	s_waitcnt lgkmcnt(0)
	v_cvt_pk_bf16_f32 v87, v88, v89
	ds_read2_b32 v[88:89], v85 offset0:4 offset1:69
	s_and_b64 vcc, s[42:43], vcc
	v_or_b32_e32 v92, s44, v70
	s_waitcnt lgkmcnt(0)
	v_cvt_pk_bf16_f32 v88, v88, v89
	ds_read2_b32 v[90:91], v85 offset0:134 offset1:199
	v_cndmask_b32_e32 v65, v65, v92, vcc
	s_waitcnt lgkmcnt(0)
	v_cvt_pk_bf16_f32 v89, v90, v91
	v_ashrrev_i32_e32 v90, 31, v65
	v_mul_lo_u32 v93, s12, v90
	v_mul_lo_u32 v94, s13, v65
	v_mad_u64_u32 v[90:91], s[52:53], s12, v65, 0
	v_add3_u32 v91, v91, v93, v94
	v_lshl_add_u64 v[90:91], v[90:91], 1, s[6:7]
	s_lshl_b64 s[40:41], s[40:41], 1
	v_lshl_add_u64 v[90:91], v[90:91], 0, s[40:41]
	v_mov_b32_e32 v65, v213
	v_lshl_add_u64 v[90:91], v[90:91], 0, v[64:65]
	global_store_dwordx4 v[90:91], v[86:89], off sc1
	ds_read2_b32 v[86:87], v69 offset0:8 offset1:73
	s_add_i32 s47, s47, s21
	s_waitcnt lgkmcnt(0)
	v_cvt_pk_bf16_f32 v86, v86, v87
	ds_read2_b32 v[88:89], v69 offset0:138 offset1:203
	s_waitcnt lgkmcnt(0)
	v_cvt_pk_bf16_f32 v87, v88, v89
	ds_read2_b32 v[88:89], v85 offset0:12 offset1:77
	s_waitcnt lgkmcnt(0)
	v_cvt_pk_bf16_f32 v88, v88, v89
	ds_read2_b32 v[90:91], v85 offset0:142 offset1:207
	s_waitcnt lgkmcnt(0)
	v_cvt_pk_bf16_f32 v89, v90, v91
	v_or_b32_e32 v90, s44, v71
	v_cmp_gt_i32_e32 vcc, s2, v90
	s_and_b64 vcc, s[42:43], vcc
	v_or_b32_e32 v91, s44, v72
	v_cndmask_b32_e32 v90, v90, v91, vcc
	v_ashrrev_i32_e32 v91, 31, v90
	v_mul_lo_u32 v93, s12, v91
	v_mul_lo_u32 v94, s13, v90
	v_mad_u64_u32 v[90:91], s[52:53], s12, v90, 0
	v_add3_u32 v91, v91, v93, v94
	v_lshl_add_u64 v[90:91], v[90:91], 1, s[6:7]
	v_lshl_add_u64 v[90:91], v[90:91], 0, s[40:41]
	v_lshl_add_u64 v[90:91], v[90:91], 0, v[64:65]
	global_store_dwordx4 v[90:91], v[86:89], off sc1
	ds_read2_b32 v[86:87], v69 offset0:16 offset1:81
	s_mov_b32 s49, s56
	s_waitcnt lgkmcnt(0)
	v_cvt_pk_bf16_f32 v86, v86, v87
	ds_read2_b32 v[88:89], v69 offset0:146 offset1:211
	s_waitcnt lgkmcnt(0)
	v_cvt_pk_bf16_f32 v87, v88, v89
	ds_read2_b32 v[88:89], v85 offset0:20 offset1:85
	s_waitcnt lgkmcnt(0)
	v_cvt_pk_bf16_f32 v88, v88, v89
	ds_read2_b32 v[90:91], v85 offset0:150 offset1:215
	s_waitcnt lgkmcnt(0)
; #define LAS __attribute__((address_space(3)))
; __device__ __forceinline__ unsigned pk2(float lo, float hi) { return pg8::cvt_pk_bf16(lo, hi); }
; __device__ __forceinline__ void tr_store(const TrD& d, LAS float* scr, int lane) {
;     const int nblk = d.N / 64, kb = d.item / nblk, nb = d.item % nblk, k0 = 64 * kb, n0 = 64 * nb, c = lane & 7;
; #pragma unroll
;     for (int j = 0; j < 8; ++j) { const int n = (lane >> 3) + 8 * j; const LAS float* s = scr + (8 * c) * 65 + n;
;         v4u o; o.x = pk2(s[0 * 65], s[1 * 65]); o.y = pk2(s[2 * 65], s[3 * 65]); o.z = pk2(s[4 * 65], s[5 * 65]); o.w = pk2(s[6 * 65], s[7 * 65]);
;         int dn = n0 + n; if (d.perm && dn < 1536) { const int f = dn & 127; dn = (dn & ~127) | ((f >> 6) * 64 + 2 * (f & 31) + ((f >> 5) & 1)); }
;         __builtin_nontemporal_store(o, (v4u*)(d.WT + (size_t)dn * d.K + k0 + 8 * c)); }
;     asm volatile("s_waitcnt lgkmcnt(0)" ::: "memory");
; }
	v_cvt_pk_bf16_f32 v89, v90, v91
	v_or_b32_e32 v90, s44, v73
	v_cmp_gt_i32_e32 vcc, s2, v90
	s_and_b64 vcc, s[42:43], vcc
	v_or_b32_e32 v91, s44, v74
	v_cndmask_b32_e32 v90, v90, v91, vcc
	v_ashrrev_i32_e32 v91, 31, v90
	v_mul_lo_u32 v93, s12, v91
	v_mul_lo_u32 v94, s13, v90
	v_mad_u64_u32 v[90:91], s[52:53], s12, v90, 0
	v_add3_u32 v91, v91, v93, v94
	v_lshl_add_u64 v[90:91], v[90:91], 1, s[6:7]
	v_lshl_add_u64 v[90:91], v[90:91], 0, s[40:41]
	v_lshl_add_u64 v[90:91], v[90:91], 0, v[64:65]
	global_store_dwordx4 v[90:91], v[86:89], off sc1
	ds_read2_b32 v[86:87], v69 offset0:24 offset1:89
	s_mov_b32 s51, s50
	s_waitcnt lgkmcnt(0)
	v_cvt_pk_bf16_f32 v86, v86, v87
	ds_read2_b32 v[88:89], v69 offset0:154 offset1:219
	s_waitcnt lgkmcnt(0)
	v_cvt_pk_bf16_f32 v87, v88, v89
	ds_read2_b32 v[88:89], v85 offset0:28 offset1:93
	s_waitcnt lgkmcnt(0)
	v_cvt_pk_bf16_f32 v88, v88, v89
	ds_read2_b32 v[90:91], v85 offset0:158 offset1:223
	s_waitcnt lgkmcnt(0)
	v_cvt_pk_bf16_f32 v89, v90, v91
	v_or_b32_e32 v90, s44, v75
	v_cmp_gt_i32_e32 vcc, s2, v90
	s_and_b64 vcc, s[42:43], vcc
	v_or_b32_e32 v91, s44, v76
	v_cndmask_b32_e32 v90, v90, v91, vcc
	v_ashrrev_i32_e32 v91, 31, v90
	v_mul_lo_u32 v93, s12, v91
	v_mul_lo_u32 v94, s13, v90
	v_mad_u64_u32 v[90:91], s[52:53], s12, v90, 0
	v_add3_u32 v91, v91, v93, v94
	v_lshl_add_u64 v[90:91], v[90:91], 1, s[6:7]
	v_lshl_add_u64 v[90:91], v[90:91], 0, s[40:41]
	v_lshl_add_u64 v[90:91], v[90:91], 0, v[64:65]
	global_store_dwordx4 v[90:91], v[86:89], off sc1
	ds_read2_b32 v[86:87], v69 offset0:32 offset1:97
	s_waitcnt lgkmcnt(0)
	v_cvt_pk_bf16_f32 v86, v86, v87
	ds_read2_b32 v[88:89], v69 offset0:162 offset1:227
	s_waitcnt lgkmcnt(0)
	v_cvt_pk_bf16_f32 v87, v88, v89
	ds_read2_b32 v[88:89], v85 offset0:36 offset1:101
	s_waitcnt lgkmcnt(0)
	v_cvt_pk_bf16_f32 v88, v88, v89
	ds_read2_b32 v[90:91], v85 offset0:166 offset1:231
	s_waitcnt lgkmcnt(0)
	v_cvt_pk_bf16_f32 v89, v90, v91
	v_or_b32_e32 v90, s44, v77
	v_cmp_gt_i32_e32 vcc, s2, v90
	s_and_b64 vcc, s[42:43], vcc
	v_or_b32_e32 v91, 1, v92
	v_cndmask_b32_e32 v90, v90, v91, vcc
	v_ashrrev_i32_e32 v91, 31, v90
	v_mul_lo_u32 v92, s12, v91
	v_mul_lo_u32 v93, s13, v90
	v_mad_u64_u32 v[90:91], s[52:53], s12, v90, 0
	v_add3_u32 v91, v91, v92, v93
	v_lshl_add_u64 v[90:91], v[90:91], 1, s[6:7]
	v_lshl_add_u64 v[90:91], v[90:91], 0, s[40:41]
	v_lshl_add_u64 v[90:91], v[90:91], 0, v[64:65]
	global_store_dwordx4 v[90:91], v[86:89], off sc1
	ds_read2_b32 v[86:87], v69 offset0:40 offset1:105
	s_waitcnt lgkmcnt(0)
	v_cvt_pk_bf16_f32 v86, v86, v87
	ds_read2_b32 v[88:89], v69 offset0:170 offset1:235
	s_waitcnt lgkmcnt(0)
	v_cvt_pk_bf16_f32 v87, v88, v89
	ds_read2_b32 v[88:89], v85 offset0:44 offset1:109
	s_waitcnt lgkmcnt(0)
	v_cvt_pk_bf16_f32 v88, v88, v89
	ds_read2_b32 v[90:91], v85 offset0:174 offset1:239
	s_waitcnt lgkmcnt(0)
	v_cvt_pk_bf16_f32 v89, v90, v91
	v_or_b32_e32 v90, s44, v78
	v_cmp_gt_i32_e32 vcc, s2, v90
	s_and_b64 vcc, s[42:43], vcc
	v_or_b32_e32 v91, s44, v79
	v_cndmask_b32_e32 v90, v90, v91, vcc
	v_ashrrev_i32_e32 v91, 31, v90
	v_mul_lo_u32 v92, s12, v91
	v_mul_lo_u32 v93, s13, v90
	v_mad_u64_u32 v[90:91], s[52:53], s12, v90, 0
	v_add3_u32 v91, v91, v92, v93
	v_lshl_add_u64 v[90:91], v[90:91], 1, s[6:7]
	v_lshl_add_u64 v[90:91], v[90:91], 0, s[40:41]
	v_lshl_add_u64 v[90:91], v[90:91], 0, v[64:65]
	global_store_dwordx4 v[90:91], v[86:89], off sc1
	ds_read2_b32 v[86:87], v69 offset0:48 offset1:113
	s_waitcnt lgkmcnt(0)
	v_cvt_pk_bf16_f32 v86, v86, v87
	ds_read2_b32 v[88:89], v69 offset0:178 offset1:243
	s_waitcnt lgkmcnt(0)
	v_cvt_pk_bf16_f32 v87, v88, v89
	ds_read2_b32 v[88:89], v85 offset0:52 offset1:117
	s_waitcnt lgkmcnt(0)
	v_cvt_pk_bf16_f32 v88, v88, v89
	ds_read2_b32 v[90:91], v85 offset0:182 offset1:247
	s_waitcnt lgkmcnt(0)
	v_cvt_pk_bf16_f32 v89, v90, v91
	v_or_b32_e32 v90, s44, v80
	v_cmp_gt_i32_e32 vcc, s2, v90
	s_and_b64 vcc, s[42:43], vcc
	v_or_b32_e32 v91, s44, v81
	v_cndmask_b32_e32 v90, v90, v91, vcc
	v_ashrrev_i32_e32 v91, 31, v90
	v_mul_lo_u32 v92, s12, v91
	v_mul_lo_u32 v93, s13, v90
	v_mad_u64_u32 v[90:91], s[52:53], s12, v90, 0
	v_add3_u32 v91, v91, v92, v93
	v_lshl_add_u64 v[90:91], v[90:91], 1, s[6:7]
	v_lshl_add_u64 v[90:91], v[90:91], 0, s[40:41]
	v_lshl_add_u64 v[90:91], v[90:91], 0, v[64:65]
	global_store_dwordx4 v[90:91], v[86:89], off sc1
	ds_read2_b32 v[86:87], v69 offset0:56 offset1:121
	s_waitcnt lgkmcnt(0)
	v_cvt_pk_bf16_f32 v86, v86, v87
	ds_read2_b32 v[88:89], v69 offset0:186 offset1:251
	s_waitcnt lgkmcnt(0)
	v_cvt_pk_bf16_f32 v87, v88, v89
	ds_read2_b32 v[88:89], v85 offset0:60 offset1:125
	s_waitcnt lgkmcnt(0)
	v_cvt_pk_bf16_f32 v88, v88, v89
	ds_read2_b32 v[90:91], v85 offset0:190 offset1:255
	v_or_b32_e32 v85, s44, v82
	v_cmp_gt_i32_e32 vcc, s2, v85
	s_waitcnt lgkmcnt(0)
	v_cvt_pk_bf16_f32 v89, v90, v91
	s_and_b64 vcc, s[42:43], vcc
	v_or_b32_e32 v90, s44, v83
	v_cndmask_b32_e32 v85, v85, v90, vcc
	v_ashrrev_i32_e32 v90, 31, v85
	v_mul_lo_u32 v92, s12, v90
	v_mul_lo_u32 v93, s13, v85
	v_mad_u64_u32 v[90:91], s[12:13], s12, v85, 0
	v_add3_u32 v91, v91, v92, v93
	v_lshl_add_u64 v[90:91], v[90:91], 1, s[6:7]
	v_lshl_add_u64 v[90:91], v[90:91], 0, s[40:41]
	v_lshl_add_u64 v[90:91], v[90:91], 0, v[64:65]
	global_store_dwordx4 v[90:91], v[86:89], off sc1
	s_waitcnt lgkmcnt(0)
	s_add_i32 s2, s46, s47
	s_cmpk_gt_i32 s2, 0x2ff
	s_mov_b32 s40, s8
	s_mov_b64 s[12:13], s[38:39]
	s_mov_b64 s[6:7], s[36:37]
	s_cbranch_scc1 .LBB0_1539

; #define LAS __attribute__((address_space(3)))
; __device__ __forceinline__ unsigned pk2(float lo, float hi) { return pg8::cvt_pk_bf16(lo, hi); }
; __device__ __forceinline__ void tr_load(const TrD& d, int lane, f32x4 (&v)[16]) {
;     const int nblk = d.N / 64, kb = d.item / nblk, nb = d.item % nblk, k0 = 64 * kb, n0 = 64 * nb, lr = lane >> 4, lc = (lane & 15) * 4;
;     const float* src = d.W + (size_t)(k0 + lr) * d.N + n0 + lc;
; #pragma unroll
;     for (int i = 0; i < 16; ++i) v[i] = __builtin_nontemporal_load((const f32x4*)(src + (size_t)(4 * i) * d.N));
; }
; __device__ __forceinline__ void tr_lds_write(LAS float* scr, int lane, const f32x4 (&v)[16]) {
;     const int lr = lane >> 4, lc = (lane & 15) * 4;
; #pragma unroll
;     for (int i = 0; i < 16; ++i) { const int kk = 4 * i + lr; scr[kk * 65 + lc + 0] = v[i][0]; scr[kk * 65 + lc + 1] = v[i][1]; scr[kk * 65 + lc + 2] = v[i][2]; scr[kk * 65 + lc + 3] = v[i][3]; }
;     asm volatile("s_waitcnt lgkmcnt(0)" ::: "memory");
; }
; __device__ __forceinline__ void tr_store(const TrD& d, LAS float* scr, int lane) {
;     const int nblk = d.N / 64, kb = d.item / nblk, nb = d.item % nblk, k0 = 64 * kb, n0 = 64 * nb, c = lane & 7;
; #pragma unroll
;     for (int j = 0; j < 8; ++j) { const int n = (lane >> 3) + 8 * j; const LAS float* s = scr + (8 * c) * 65 + n;
;         v4u o; o.x = pk2(s[0 * 65], s[1 * 65]); o.y = pk2(s[2 * 65], s[3 * 65]); o.z = pk2(s[4 * 65], s[5 * 65]); o.w = pk2(s[6 * 65], s[7 * 65]);
;         int dn = n0 + n; if (d.perm && dn < 1536) { const int f = dn & 127; dn = (dn & ~127) | ((f >> 6) * 64 + 2 * (f & 31) + ((f >> 5) & 1)); }
;         __builtin_nontemporal_store(o, (v4u*)(d.WT + (size_t)dn * d.K + k0 + 8 * c)); }
.LBB0_1739:
	s_lshr_b32 s16, s8, 6
	v_cvt_f32_i32_e32 v1, s16
	s_sext_i32_i16 s30, s21
	v_cvt_f32_i32_e32 v0, s30
	s_ashr_i32 s39, s30, 30
	v_rcp_iflag_f32_e32 v2, v1
	s_or_b32 s39, s39, 1
	v_mul_f32_e32 v2, v0, v2
	v_trunc_f32_e32 v2, v2
	v_fma_f32 v0, -v2, v1, v0
	v_cvt_i32_f32_e32 v2, v2
	v_cmp_ge_f32_e64 s[42:43], |v0|, v1
	s_and_b64 s[42:43], s[42:43], exec
	s_cselect_b32 s30, s39, 0
	v_readfirstlane_b32 s39, v2
	s_add_i32 s30, s39, s30
	s_sext_i32_i16 s39, s30
	s_mul_i32 s30, s30, s16
	s_sub_i32 s16, s21, s30
	s_sext_i32_i16 s16, s16
	v_lshl_or_b32 v0, s39, 6, v66
	s_lshl_b32 s42, s16, 6
	v_mul_hi_i32_i24_e32 v1, s8, v0
	v_mul_i32_i24_e32 v0, s8, v0
	s_waitcnt lgkmcnt(0)
	v_lshl_add_u64 v[0:1], v[0:1], 2, s[40:41]
	s_ashr_i32 s43, s42, 31
	v_lshl_add_u64 v[0:1], s[42:43], 2, v[0:1]
	v_lshl_add_u64 v[0:1], v[0:1], 0, v[212:213]
	s_lshl_b64 s[40:41], s[8:9], 4
	global_load_dwordx4 v[52:55], v[0:1], off nt
	v_lshl_add_u64 v[0:1], v[0:1], 0, s[40:41]
	global_load_dwordx4 v[60:63], v[0:1], off nt
	v_lshl_add_u64 v[0:1], v[0:1], 0, s[40:41]
	s_lshr_b32 s16, s38, 6
	global_load_dwordx4 v[44:47], v[0:1], off nt
	v_lshl_add_u64 v[0:1], v[0:1], 0, s[40:41]
	v_cvt_f32_i32_e32 v84, s16
	global_load_dwordx4 v[56:59], v[0:1], off nt
	v_lshl_add_u64 v[0:1], v[0:1], 0, s[40:41]
	global_load_dwordx4 v[36:39], v[0:1], off nt
	v_lshl_add_u64 v[0:1], v[0:1], 0, s[40:41]
	global_load_dwordx4 v[48:51], v[0:1], off nt
	v_lshl_add_u64 v[0:1], v[0:1], 0, s[40:41]
	s_sext_i32_i16 s30, s47
	global_load_dwordx4 v[32:35], v[0:1], off nt
	v_lshl_add_u64 v[0:1], v[0:1], 0, s[40:41]
	v_cvt_f32_i32_e32 v65, s30
	v_rcp_iflag_f32_e32 v85, v84
	global_load_dwordx4 v[40:43], v[0:1], off nt
	v_lshl_add_u64 v[0:1], v[0:1], 0, s[40:41]
	global_load_dwordx4 v[24:27], v[0:1], off nt
	v_lshl_add_u64 v[0:1], v[0:1], 0, s[40:41]
	global_load_dwordx4 v[20:23], v[0:1], off nt
	v_lshl_add_u64 v[0:1], v[0:1], 0, s[40:41]
	global_load_dwordx4 v[16:19], v[0:1], off nt
	v_lshl_add_u64 v[0:1], v[0:1], 0, s[40:41]
	v_mul_f32_e32 v85, v65, v85
	global_load_dwordx4 v[12:15], v[0:1], off nt
	v_lshl_add_u64 v[0:1], v[0:1], 0, s[40:41]
	v_trunc_f32_e32 v85, v85
	global_load_dwordx4 v[8:11], v[0:1], off nt
	v_lshl_add_u64 v[0:1], v[0:1], 0, s[40:41]
	v_fma_f32 v65, -v85, v84, v65
	v_cvt_i32_f32_e32 v85, v85
	v_lshl_add_u64 v[28:29], v[0:1], 0, s[40:41]
	s_ashr_i32 s38, s30, 30
	global_load_dwordx4 v[4:7], v[0:1], off nt
	s_nop 0
	global_load_dwordx4 v[0:3], v[28:29], off nt
	v_lshl_add_u64 v[28:29], v[28:29], 0, s[40:41]
	s_or_b32 s40, s38, 1
	v_cmp_ge_f32_e64 s[38:39], |v65|, v84
	s_and_b64 s[38:39], s[38:39], exec
	s_cselect_b32 s30, s40, 0
	v_readfirstlane_b32 s38, v85
	s_add_i32 s30, s38, s30
	s_sext_i32_i16 s38, s30
	s_mul_i32 s30, s30, s16
	s_sub_i32 s16, s47, s30
	s_sext_i32_i16 s16, s16
	s_lshl_b32 s38, s38, 6
	s_lshl_b32 s42, s16, 6
	s_ashr_i32 s39, s38, 31
	ds_read2_b32 v[84:85], v68 offset1:65
	global_load_dwordx4 v[28:31], v[28:29], off nt
	s_waitcnt lgkmcnt(0)
	v_cvt_pk_bf16_f32 v86, v84, v85
	ds_read2_b32 v[84:85], v68 offset0:130 offset1:195
	v_or_b32_e32 v65, s42, v67
	s_cmp_lg_u32 s46, 0
	s_movk_i32 s16, 0x600
	s_waitcnt lgkmcnt(0)
	v_cvt_pk_bf16_f32 v87, v84, v85
	v_add_u32_e32 v84, 0x400, v68
	s_cselect_b64 s[40:41], -1, 0
	v_cmp_gt_i32_e32 vcc, s16, v65
	ds_read2_b32 v[88:89], v84 offset0:4 offset1:69
	s_and_b64 vcc, s[40:41], vcc
	v_or_b32_e32 v85, s42, v69
	s_waitcnt lgkmcnt(0)
	v_cvt_pk_bf16_f32 v88, v88, v89
	ds_read2_b32 v[90:91], v84 offset0:134 offset1:199
	v_cndmask_b32_e32 v65, v65, v85, vcc
	s_waitcnt lgkmcnt(0)
	v_cvt_pk_bf16_f32 v89, v90, v91
	v_mul_hi_i32_i24_e32 v91, s12, v65
	v_mul_i32_i24_e32 v90, s12, v65
	v_lshl_add_u64 v[90:91], v[90:91], 1, s[6:7]
	s_lshl_b64 s[38:39], s[38:39], 1
	v_lshl_add_u64 v[90:91], v[90:91], 0, s[38:39]
	v_mov_b32_e32 v65, v213
	v_lshl_add_u64 v[90:91], v[90:91], 0, v[64:65]
	global_store_dwordx4 v[90:91], v[86:89], off sc1
	ds_read2_b32 v[86:87], v68 offset0:8 offset1:73
	v_or_b32_e32 v85, 1, v85
	s_waitcnt lgkmcnt(0)
	v_cvt_pk_bf16_f32 v86, v86, v87
	ds_read2_b32 v[88:89], v68 offset0:138 offset1:203
	s_waitcnt lgkmcnt(0)
	v_cvt_pk_bf16_f32 v87, v88, v89
	ds_read2_b32 v[88:89], v84 offset0:12 offset1:77
	s_waitcnt lgkmcnt(0)
	v_cvt_pk_bf16_f32 v88, v88, v89
	ds_read2_b32 v[90:91], v84 offset0:142 offset1:207
	s_waitcnt lgkmcnt(0)
	v_cvt_pk_bf16_f32 v89, v90, v91
	v_or_b32_e32 v90, s42, v70
	v_cmp_gt_i32_e32 vcc, s16, v90
	s_and_b64 vcc, s[40:41], vcc
	v_or_b32_e32 v91, s42, v71
	v_cndmask_b32_e32 v90, v90, v91, vcc
	v_ashrrev_i32_e32 v91, 31, v90
	v_mul_lo_u32 v92, s12, v91
	v_mul_lo_u32 v93, s13, v90
	v_mad_u64_u32 v[90:91], s[46:47], s12, v90, 0
	v_add3_u32 v91, v91, v92, v93
	v_lshl_add_u64 v[90:91], v[90:91], 1, s[6:7]
	v_lshl_add_u64 v[90:91], v[90:91], 0, s[38:39]
	v_lshl_add_u64 v[90:91], v[90:91], 0, v[64:65]
	global_store_dwordx4 v[90:91], v[86:89], off sc1
	ds_read2_b32 v[86:87], v68 offset0:16 offset1:81
	s_add_i32 s20, s20, s22
	s_waitcnt lgkmcnt(0)
	v_cvt_pk_bf16_f32 v86, v86, v87
	ds_read2_b32 v[88:89], v68 offset0:146 offset1:211
	s_waitcnt lgkmcnt(0)
	v_cvt_pk_bf16_f32 v87, v88, v89
	ds_read2_b32 v[88:89], v84 offset0:20 offset1:85
	s_waitcnt lgkmcnt(0)
; #define LAS __attribute__((address_space(3)))
; __device__ __forceinline__ unsigned pk2(float lo, float hi) { return pg8::cvt_pk_bf16(lo, hi); }
; __device__ __forceinline__ void tr_store(const TrD& d, LAS float* scr, int lane) {
;     const int nblk = d.N / 64, kb = d.item / nblk, nb = d.item % nblk, k0 = 64 * kb, n0 = 64 * nb, c = lane & 7;
; #pragma unroll
;     for (int j = 0; j < 8; ++j) { const int n = (lane >> 3) + 8 * j; const LAS float* s = scr + (8 * c) * 65 + n;
;         v4u o; o.x = pk2(s[0 * 65], s[1 * 65]); o.y = pk2(s[2 * 65], s[3 * 65]); o.z = pk2(s[4 * 65], s[5 * 65]); o.w = pk2(s[6 * 65], s[7 * 65]);
;         int dn = n0 + n; if (d.perm && dn < 1536) { const int f = dn & 127; dn = (dn & ~127) | ((f >> 6) * 64 + 2 * (f & 31) + ((f >> 5) & 1)); }
;         __builtin_nontemporal_store(o, (v4u*)(d.WT + (size_t)dn * d.K + k0 + 8 * c)); }
;     asm volatile("s_waitcnt lgkmcnt(0)" ::: "memory");
; }
	v_cvt_pk_bf16_f32 v88, v88, v89
	ds_read2_b32 v[90:91], v84 offset0:150 offset1:215
	s_waitcnt lgkmcnt(0)
	v_cvt_pk_bf16_f32 v89, v90, v91
	v_or_b32_e32 v90, s42, v72
	v_cmp_gt_i32_e32 vcc, s16, v90
	s_and_b64 vcc, s[40:41], vcc
	v_or_b32_e32 v91, s42, v73
	v_cndmask_b32_e32 v90, v90, v91, vcc
	v_ashrrev_i32_e32 v91, 31, v90
	v_mul_lo_u32 v92, s12, v91
	v_mul_lo_u32 v93, s13, v90
	v_mad_u64_u32 v[90:91], s[46:47], s12, v90, 0
	v_add3_u32 v91, v91, v92, v93
	v_lshl_add_u64 v[90:91], v[90:91], 1, s[6:7]
	v_lshl_add_u64 v[90:91], v[90:91], 0, s[38:39]
	v_lshl_add_u64 v[90:91], v[90:91], 0, v[64:65]
	global_store_dwordx4 v[90:91], v[86:89], off sc1
	ds_read2_b32 v[86:87], v68 offset0:24 offset1:89
	s_waitcnt lgkmcnt(0)
	v_cvt_pk_bf16_f32 v86, v86, v87
	ds_read2_b32 v[88:89], v68 offset0:154 offset1:219
	s_waitcnt lgkmcnt(0)
	v_cvt_pk_bf16_f32 v87, v88, v89
	ds_read2_b32 v[88:89], v84 offset0:28 offset1:93
	s_waitcnt lgkmcnt(0)
	v_cvt_pk_bf16_f32 v88, v88, v89
	ds_read2_b32 v[90:91], v84 offset0:158 offset1:223
	s_waitcnt lgkmcnt(0)
	v_cvt_pk_bf16_f32 v89, v90, v91
	v_or_b32_e32 v90, s42, v74
	v_cmp_gt_i32_e32 vcc, s16, v90
	s_and_b64 vcc, s[40:41], vcc
	v_or_b32_e32 v91, s42, v75
	v_cndmask_b32_e32 v90, v90, v91, vcc
	v_ashrrev_i32_e32 v91, 31, v90
	v_mul_lo_u32 v92, s12, v91
	v_mul_lo_u32 v93, s13, v90
	v_mad_u64_u32 v[90:91], s[46:47], s12, v90, 0
	v_add3_u32 v91, v91, v92, v93
	v_lshl_add_u64 v[90:91], v[90:91], 1, s[6:7]
	v_lshl_add_u64 v[90:91], v[90:91], 0, s[38:39]
	v_lshl_add_u64 v[90:91], v[90:91], 0, v[64:65]
	global_store_dwordx4 v[90:91], v[86:89], off sc1
	ds_read2_b32 v[86:87], v68 offset0:32 offset1:97
	s_waitcnt lgkmcnt(0)
	v_cvt_pk_bf16_f32 v86, v86, v87
	ds_read2_b32 v[88:89], v68 offset0:162 offset1:227
	s_waitcnt lgkmcnt(0)
	v_cvt_pk_bf16_f32 v87, v88, v89
	ds_read2_b32 v[88:89], v84 offset0:36 offset1:101
	s_waitcnt lgkmcnt(0)
	v_cvt_pk_bf16_f32 v88, v88, v89
	ds_read2_b32 v[90:91], v84 offset0:166 offset1:231
	s_waitcnt lgkmcnt(0)
	v_cvt_pk_bf16_f32 v89, v90, v91
	v_or_b32_e32 v90, s42, v76
	v_cmp_gt_i32_e32 vcc, s16, v90
	s_and_b64 vcc, s[40:41], vcc
	s_nop 0
	v_cndmask_b32_e32 v85, v90, v85, vcc
	v_ashrrev_i32_e32 v90, 31, v85
	v_mul_lo_u32 v92, s12, v90
	v_mul_lo_u32 v93, s13, v85
	v_mad_u64_u32 v[90:91], s[46:47], s12, v85, 0
	v_add3_u32 v91, v91, v92, v93
	v_lshl_add_u64 v[90:91], v[90:91], 1, s[6:7]
	v_lshl_add_u64 v[90:91], v[90:91], 0, s[38:39]
	v_lshl_add_u64 v[90:91], v[90:91], 0, v[64:65]
	global_store_dwordx4 v[90:91], v[86:89], off sc1
	ds_read2_b32 v[86:87], v68 offset0:40 offset1:105
	v_or_b32_e32 v85, s42, v77
	s_waitcnt lgkmcnt(0)
	v_cvt_pk_bf16_f32 v86, v86, v87
	ds_read2_b32 v[88:89], v68 offset0:170 offset1:235
	s_waitcnt lgkmcnt(0)
	v_cvt_pk_bf16_f32 v87, v88, v89
	ds_read2_b32 v[88:89], v84 offset0:44 offset1:109
	s_waitcnt lgkmcnt(0)
	v_cvt_pk_bf16_f32 v88, v88, v89
	ds_read2_b32 v[90:91], v84 offset0:174 offset1:239
	v_cmp_gt_i32_e32 vcc, s16, v85
	s_waitcnt lgkmcnt(0)
	v_cvt_pk_bf16_f32 v89, v90, v91
	s_and_b64 vcc, s[40:41], vcc
	v_or_b32_e32 v90, s42, v78
	v_cndmask_b32_e32 v85, v85, v90, vcc
	v_mul_hi_i32_i24_e32 v91, s12, v85
	v_mul_i32_i24_e32 v90, s12, v85
	v_lshl_add_u64 v[90:91], v[90:91], 1, s[6:7]
	v_lshl_add_u64 v[90:91], v[90:91], 0, s[38:39]
	v_lshl_add_u64 v[90:91], v[90:91], 0, v[64:65]
	global_store_dwordx4 v[90:91], v[86:89], off sc1
	ds_read2_b32 v[86:87], v68 offset0:48 offset1:113
	v_or_b32_e32 v85, s42, v79
	s_waitcnt lgkmcnt(0)
	v_cvt_pk_bf16_f32 v86, v86, v87
	ds_read2_b32 v[88:89], v68 offset0:178 offset1:243
	s_waitcnt lgkmcnt(0)
	v_cvt_pk_bf16_f32 v87, v88, v89
	ds_read2_b32 v[88:89], v84 offset0:52 offset1:117
	s_waitcnt lgkmcnt(0)
	v_cvt_pk_bf16_f32 v88, v88, v89
	ds_read2_b32 v[90:91], v84 offset0:182 offset1:247
	v_cmp_gt_i32_e32 vcc, s16, v85
	s_waitcnt lgkmcnt(0)
	v_cvt_pk_bf16_f32 v89, v90, v91
	s_and_b64 vcc, s[40:41], vcc
	v_or_b32_e32 v90, s42, v80
	v_cndmask_b32_e32 v85, v85, v90, vcc
	v_mul_hi_i32_i24_e32 v91, s12, v85
	v_mul_i32_i24_e32 v90, s12, v85
	v_lshl_add_u64 v[90:91], v[90:91], 1, s[6:7]
	v_lshl_add_u64 v[90:91], v[90:91], 0, s[38:39]
	v_lshl_add_u64 v[90:91], v[90:91], 0, v[64:65]
	global_store_dwordx4 v[90:91], v[86:89], off sc1
	ds_read2_b32 v[86:87], v68 offset0:56 offset1:121
	s_mov_b32 s47, s21
	s_waitcnt lgkmcnt(0)
	v_cvt_pk_bf16_f32 v86, v86, v87
	ds_read2_b32 v[88:89], v68 offset0:186 offset1:251
	s_waitcnt lgkmcnt(0)
	v_cvt_pk_bf16_f32 v87, v88, v89
	ds_read2_b32 v[88:89], v84 offset0:60 offset1:125
	s_waitcnt lgkmcnt(0)
	v_cvt_pk_bf16_f32 v88, v88, v89
	ds_read2_b32 v[84:85], v84 offset0:190 offset1:255
	s_waitcnt lgkmcnt(0)
	v_cvt_pk_bf16_f32 v89, v84, v85
	v_or_b32_e32 v84, s42, v81
	v_cmp_gt_i32_e32 vcc, s16, v84
	s_and_b64 vcc, s[40:41], vcc
	v_or_b32_e32 v85, s42, v82
	v_cndmask_b32_e32 v84, v84, v85, vcc
	v_mul_hi_i32_i24_e32 v85, s12, v84
	v_mul_i32_i24_e32 v84, s12, v84
	v_lshl_add_u64 v[84:85], v[84:85], 1, s[6:7]
	v_lshl_add_u64 v[84:85], v[84:85], 0, s[38:39]
	v_lshl_add_u64 v[84:85], v[84:85], 0, v[64:65]
	global_store_dwordx4 v[84:85], v[86:89], off sc1
	s_waitcnt lgkmcnt(0)
	s_add_i32 s6, s45, s20
	s_cmpk_lt_i32 s6, 0x1000
	s_mov_b64 s[6:7], s[2:3]
	s_mov_b64 s[12:13], s[36:37]
	s_mov_b32 s38, s8
	s_mov_b32 s46, s48
	s_cbranch_scc0 .LBB0_1776

; #define LAS __attribute__((address_space(3)))
; __device__ __forceinline__ unsigned pk2(float lo, float hi) { return pg8::cvt_pk_bf16(lo, hi); }
; __device__ __forceinline__ void tr_load(const TrD& d, int lane, f32x4 (&v)[16]) {
;     const int nblk = d.N / 64, kb = d.item / nblk, nb = d.item % nblk, k0 = 64 * kb, n0 = 64 * nb, lr = lane >> 4, lc = (lane & 15) * 4;
;     const float* src = d.W + (size_t)(k0 + lr) * d.N + n0 + lc;
; #pragma unroll
;     for (int i = 0; i < 16; ++i) v[i] = __builtin_nontemporal_load((const f32x4*)(src + (size_t)(4 * i) * d.N));
; }
; __device__ __forceinline__ void tr_lds_write(LAS float* scr, int lane, const f32x4 (&v)[16]) {
;     const int lr = lane >> 4, lc = (lane & 15) * 4;
; #pragma unroll
;     for (int i = 0; i < 16; ++i) { const int kk = 4 * i + lr; scr[kk * 65 + lc + 0] = v[i][0]; scr[kk * 65 + lc + 1] = v[i][1]; scr[kk * 65 + lc + 2] = v[i][2]; scr[kk * 65 + lc + 3] = v[i][3]; }
;     asm volatile("s_waitcnt lgkmcnt(0)" ::: "memory");
; }
; __device__ __forceinline__ void tr_store(const TrD& d, LAS float* scr, int lane) {
;     const int nblk = d.N / 64, kb = d.item / nblk, nb = d.item % nblk, k0 = 64 * kb, n0 = 64 * nb, c = lane & 7;
; #pragma unroll
;     for (int j = 0; j < 8; ++j) { const int n = (lane >> 3) + 8 * j; const LAS float* s = scr + (8 * c) * 65 + n;
;         v4u o; o.x = pk2(s[0 * 65], s[1 * 65]); o.y = pk2(s[2 * 65], s[3 * 65]); o.z = pk2(s[4 * 65], s[5 * 65]); o.w = pk2(s[6 * 65], s[7 * 65]);
;         int dn = n0 + n; if (d.perm && dn < 1536) { const int f = dn & 127; dn = (dn & ~127) | ((f >> 6) * 64 + 2 * (f & 31) + ((f >> 5) & 1)); }
;         __builtin_nontemporal_store(o, (v4u*)(d.WT + (size_t)dn * d.K + k0 + 8 * c)); }
.LBB0_2015:
	s_lshr_b32 s16, s8, 6
	v_cvt_f32_i32_e32 v1, s16
	s_sext_i32_i16 s30, s50
	v_cvt_f32_i32_e32 v0, s30
	s_ashr_i32 s39, s30, 30
	v_rcp_iflag_f32_e32 v2, v1
	s_or_b32 s39, s39, 1
	v_mul_f32_e32 v2, v0, v2
	v_trunc_f32_e32 v2, v2
	v_fma_f32 v0, -v2, v1, v0
	v_cvt_i32_f32_e32 v2, v2
	v_cmp_ge_f32_e64 s[42:43], |v0|, v1
	s_and_b64 s[42:43], s[42:43], exec
	s_cselect_b32 s30, s39, 0
	v_readfirstlane_b32 s39, v2
	s_add_i32 s30, s39, s30
	s_sext_i32_i16 s39, s30
	s_mul_i32 s30, s30, s16
	s_sub_i32 s16, s50, s30
	s_sext_i32_i16 s16, s16
	v_lshl_or_b32 v0, s39, 6, v67
	s_lshl_b32 s42, s16, 6
	v_mul_hi_i32_i24_e32 v1, s8, v0
	v_mul_i32_i24_e32 v0, s8, v0
	s_waitcnt lgkmcnt(0)
	v_lshl_add_u64 v[0:1], v[0:1], 2, s[40:41]
	s_ashr_i32 s43, s42, 31
	v_lshl_add_u64 v[0:1], s[42:43], 2, v[0:1]
	v_lshl_add_u64 v[0:1], v[0:1], 0, v[212:213]
	s_lshl_b64 s[40:41], s[8:9], 4
	global_load_dwordx4 v[52:55], v[0:1], off nt
	v_lshl_add_u64 v[0:1], v[0:1], 0, s[40:41]
	global_load_dwordx4 v[60:63], v[0:1], off nt
	v_lshl_add_u64 v[0:1], v[0:1], 0, s[40:41]
	s_lshr_b32 s16, s38, 6
	global_load_dwordx4 v[44:47], v[0:1], off nt
	v_lshl_add_u64 v[0:1], v[0:1], 0, s[40:41]
	v_cvt_f32_i32_e32 v85, s16
	global_load_dwordx4 v[56:59], v[0:1], off nt
	v_lshl_add_u64 v[0:1], v[0:1], 0, s[40:41]
	global_load_dwordx4 v[36:39], v[0:1], off nt
	v_lshl_add_u64 v[0:1], v[0:1], 0, s[40:41]
	global_load_dwordx4 v[48:51], v[0:1], off nt
	v_lshl_add_u64 v[0:1], v[0:1], 0, s[40:41]
	s_sext_i32_i16 s30, s51
	global_load_dwordx4 v[32:35], v[0:1], off nt
	v_lshl_add_u64 v[0:1], v[0:1], 0, s[40:41]
	v_cvt_f32_i32_e32 v65, s30
	v_rcp_iflag_f32_e32 v86, v85
	global_load_dwordx4 v[40:43], v[0:1], off nt
	v_lshl_add_u64 v[0:1], v[0:1], 0, s[40:41]
	global_load_dwordx4 v[24:27], v[0:1], off nt
	v_lshl_add_u64 v[0:1], v[0:1], 0, s[40:41]
	global_load_dwordx4 v[20:23], v[0:1], off nt
	v_lshl_add_u64 v[0:1], v[0:1], 0, s[40:41]
	global_load_dwordx4 v[16:19], v[0:1], off nt
	v_lshl_add_u64 v[0:1], v[0:1], 0, s[40:41]
	v_mul_f32_e32 v86, v65, v86
	global_load_dwordx4 v[12:15], v[0:1], off nt
	v_lshl_add_u64 v[0:1], v[0:1], 0, s[40:41]
	v_trunc_f32_e32 v86, v86
	global_load_dwordx4 v[8:11], v[0:1], off nt
	v_lshl_add_u64 v[0:1], v[0:1], 0, s[40:41]
	v_fma_f32 v65, -v86, v85, v65
	v_cvt_i32_f32_e32 v86, v86
	v_lshl_add_u64 v[28:29], v[0:1], 0, s[40:41]
	s_ashr_i32 s38, s30, 30
	global_load_dwordx4 v[4:7], v[0:1], off nt
	s_nop 0
	global_load_dwordx4 v[0:3], v[28:29], off nt
	v_lshl_add_u64 v[28:29], v[28:29], 0, s[40:41]
	s_or_b32 s40, s38, 1
	v_cmp_ge_f32_e64 s[38:39], |v65|, v85
	s_and_b64 s[38:39], s[38:39], exec
	s_cselect_b32 s30, s40, 0
	v_readfirstlane_b32 s38, v86
	s_add_i32 s30, s38, s30
	s_sext_i32_i16 s38, s30
	s_mul_i32 s30, s30, s16
	s_sub_i32 s16, s51, s30
	s_sext_i32_i16 s16, s16
	s_lshl_b32 s38, s38, 6
	s_lshl_b32 s42, s16, 6
	s_ashr_i32 s39, s38, 31
	ds_read2_b32 v[86:87], v69 offset1:65
	v_or_b32_e32 v65, s42, v68
	s_cmp_lg_u32 s49, 0
	s_movk_i32 s16, 0x600
	global_load_dwordx4 v[28:31], v[28:29], off nt
	s_waitcnt lgkmcnt(0)
	v_cvt_pk_bf16_f32 v86, v86, v87
	ds_read2_b32 v[88:89], v69 offset0:130 offset1:195
	v_add_u32_e32 v85, 0x400, v69
	s_cselect_b64 s[40:41], -1, 0
	v_cmp_gt_i32_e32 vcc, s16, v65
	s_waitcnt lgkmcnt(0)
	v_cvt_pk_bf16_f32 v87, v88, v89
	ds_read2_b32 v[88:89], v85 offset0:4 offset1:69
	s_and_b64 vcc, s[40:41], vcc
	v_or_b32_e32 v92, s42, v70
	s_waitcnt lgkmcnt(0)
	v_cvt_pk_bf16_f32 v88, v88, v89
	ds_read2_b32 v[90:91], v85 offset0:134 offset1:199
	v_cndmask_b32_e32 v65, v65, v92, vcc
	s_waitcnt lgkmcnt(0)
	v_cvt_pk_bf16_f32 v89, v90, v91
	v_mul_hi_i32_i24_e32 v91, s6, v65
	v_mul_i32_i24_e32 v90, s6, v65
	v_lshl_add_u64 v[90:91], v[90:91], 1, s[2:3]
	s_lshl_b64 s[38:39], s[38:39], 1
	v_lshl_add_u64 v[90:91], v[90:91], 0, s[38:39]
	v_mov_b32_e32 v65, v213
	v_lshl_add_u64 v[90:91], v[90:91], 0, v[64:65]
	global_store_dwordx4 v[90:91], v[86:89], off sc1
	ds_read2_b32 v[86:87], v69 offset0:8 offset1:73
	s_add_i32 s47, s47, s21
	s_waitcnt lgkmcnt(0)
	v_cvt_pk_bf16_f32 v86, v86, v87
	ds_read2_b32 v[88:89], v69 offset0:138 offset1:203
	s_waitcnt lgkmcnt(0)
	v_cvt_pk_bf16_f32 v87, v88, v89
	ds_read2_b32 v[88:89], v85 offset0:12 offset1:77
	s_waitcnt lgkmcnt(0)
	v_cvt_pk_bf16_f32 v88, v88, v89
	ds_read2_b32 v[90:91], v85 offset0:142 offset1:207
	s_waitcnt lgkmcnt(0)
	v_cvt_pk_bf16_f32 v89, v90, v91
	v_or_b32_e32 v90, s42, v71
	v_cmp_gt_i32_e32 vcc, s16, v90
	s_and_b64 vcc, s[40:41], vcc
	v_or_b32_e32 v91, s42, v72
	v_cndmask_b32_e32 v90, v90, v91, vcc
	v_ashrrev_i32_e32 v91, 31, v90
	v_mul_lo_u32 v93, s6, v91
	v_mul_lo_u32 v94, s7, v90
	v_mad_u64_u32 v[90:91], s[52:53], s6, v90, 0
	v_add3_u32 v91, v91, v93, v94
	v_lshl_add_u64 v[90:91], v[90:91], 1, s[2:3]
	v_lshl_add_u64 v[90:91], v[90:91], 0, s[38:39]
	v_lshl_add_u64 v[90:91], v[90:91], 0, v[64:65]
	global_store_dwordx4 v[90:91], v[86:89], off sc1
	ds_read2_b32 v[86:87], v69 offset0:16 offset1:81
	s_mov_b32 s51, s50
	s_waitcnt lgkmcnt(0)
	v_cvt_pk_bf16_f32 v86, v86, v87
	ds_read2_b32 v[88:89], v69 offset0:146 offset1:211
	s_waitcnt lgkmcnt(0)
	v_cvt_pk_bf16_f32 v87, v88, v89
	ds_read2_b32 v[88:89], v85 offset0:20 offset1:85
	s_waitcnt lgkmcnt(0)
; #define LAS __attribute__((address_space(3)))
; __device__ __forceinline__ unsigned pk2(float lo, float hi) { return pg8::cvt_pk_bf16(lo, hi); }
; __device__ __forceinline__ void tr_store(const TrD& d, LAS float* scr, int lane) {
;     const int nblk = d.N / 64, kb = d.item / nblk, nb = d.item % nblk, k0 = 64 * kb, n0 = 64 * nb, c = lane & 7;
; #pragma unroll
;     for (int j = 0; j < 8; ++j) { const int n = (lane >> 3) + 8 * j; const LAS float* s = scr + (8 * c) * 65 + n;
;         v4u o; o.x = pk2(s[0 * 65], s[1 * 65]); o.y = pk2(s[2 * 65], s[3 * 65]); o.z = pk2(s[4 * 65], s[5 * 65]); o.w = pk2(s[6 * 65], s[7 * 65]);
;         int dn = n0 + n; if (d.perm && dn < 1536) { const int f = dn & 127; dn = (dn & ~127) | ((f >> 6) * 64 + 2 * (f & 31) + ((f >> 5) & 1)); }
;         __builtin_nontemporal_store(o, (v4u*)(d.WT + (size_t)dn * d.K + k0 + 8 * c)); }
;     asm volatile("s_waitcnt lgkmcnt(0)" ::: "memory");
; }
	v_cvt_pk_bf16_f32 v88, v88, v89
	ds_read2_b32 v[90:91], v85 offset0:150 offset1:215
	s_waitcnt lgkmcnt(0)
	v_cvt_pk_bf16_f32 v89, v90, v91
	v_or_b32_e32 v90, s42, v73
	v_cmp_gt_i32_e32 vcc, s16, v90
	s_and_b64 vcc, s[40:41], vcc
	v_or_b32_e32 v91, s42, v74
	v_cndmask_b32_e32 v90, v90, v91, vcc
	v_ashrrev_i32_e32 v91, 31, v90
	v_mul_lo_u32 v93, s6, v91
	v_mul_lo_u32 v94, s7, v90
	v_mad_u64_u32 v[90:91], s[52:53], s6, v90, 0
	v_add3_u32 v91, v91, v93, v94
	v_lshl_add_u64 v[90:91], v[90:91], 1, s[2:3]
	v_lshl_add_u64 v[90:91], v[90:91], 0, s[38:39]
	v_lshl_add_u64 v[90:91], v[90:91], 0, v[64:65]
	global_store_dwordx4 v[90:91], v[86:89], off sc1
	ds_read2_b32 v[86:87], v69 offset0:24 offset1:89
	s_mov_b32 s49, s56
	s_waitcnt lgkmcnt(0)
	v_cvt_pk_bf16_f32 v86, v86, v87
	ds_read2_b32 v[88:89], v69 offset0:154 offset1:219
	s_waitcnt lgkmcnt(0)
	v_cvt_pk_bf16_f32 v87, v88, v89
	ds_read2_b32 v[88:89], v85 offset0:28 offset1:93
	s_waitcnt lgkmcnt(0)
	v_cvt_pk_bf16_f32 v88, v88, v89
	ds_read2_b32 v[90:91], v85 offset0:158 offset1:223
	s_waitcnt lgkmcnt(0)
	v_cvt_pk_bf16_f32 v89, v90, v91
	v_or_b32_e32 v90, s42, v75
	v_cmp_gt_i32_e32 vcc, s16, v90
	s_and_b64 vcc, s[40:41], vcc
	v_or_b32_e32 v91, s42, v76
	v_cndmask_b32_e32 v90, v90, v91, vcc
	v_ashrrev_i32_e32 v91, 31, v90
	v_mul_lo_u32 v93, s6, v91
	v_mul_lo_u32 v94, s7, v90
	v_mad_u64_u32 v[90:91], s[52:53], s6, v90, 0
	v_add3_u32 v91, v91, v93, v94
	v_lshl_add_u64 v[90:91], v[90:91], 1, s[2:3]
	v_lshl_add_u64 v[90:91], v[90:91], 0, s[38:39]
	v_lshl_add_u64 v[90:91], v[90:91], 0, v[64:65]
	global_store_dwordx4 v[90:91], v[86:89], off sc1
	ds_read2_b32 v[86:87], v69 offset0:32 offset1:97
	s_waitcnt lgkmcnt(0)
	v_cvt_pk_bf16_f32 v86, v86, v87
	ds_read2_b32 v[88:89], v69 offset0:162 offset1:227
	s_waitcnt lgkmcnt(0)
	v_cvt_pk_bf16_f32 v87, v88, v89
	ds_read2_b32 v[88:89], v85 offset0:36 offset1:101
	s_waitcnt lgkmcnt(0)
	v_cvt_pk_bf16_f32 v88, v88, v89
	ds_read2_b32 v[90:91], v85 offset0:166 offset1:231
	s_waitcnt lgkmcnt(0)
	v_cvt_pk_bf16_f32 v89, v90, v91
	v_or_b32_e32 v90, s42, v77
	v_cmp_gt_i32_e32 vcc, s16, v90
	s_and_b64 vcc, s[40:41], vcc
	v_or_b32_e32 v91, 1, v92
	v_cndmask_b32_e32 v90, v90, v91, vcc
	v_ashrrev_i32_e32 v91, 31, v90
	v_mul_lo_u32 v92, s6, v91
	v_mul_lo_u32 v93, s7, v90
	v_mad_u64_u32 v[90:91], s[52:53], s6, v90, 0
	v_add3_u32 v91, v91, v92, v93
	v_lshl_add_u64 v[90:91], v[90:91], 1, s[2:3]
	v_lshl_add_u64 v[90:91], v[90:91], 0, s[38:39]
	v_lshl_add_u64 v[90:91], v[90:91], 0, v[64:65]
	global_store_dwordx4 v[90:91], v[86:89], off sc1
	ds_read2_b32 v[86:87], v69 offset0:40 offset1:105
	s_waitcnt lgkmcnt(0)
	v_cvt_pk_bf16_f32 v86, v86, v87
	ds_read2_b32 v[88:89], v69 offset0:170 offset1:235
	s_waitcnt lgkmcnt(0)
	v_cvt_pk_bf16_f32 v87, v88, v89
	ds_read2_b32 v[88:89], v85 offset0:44 offset1:109
	s_waitcnt lgkmcnt(0)
	v_cvt_pk_bf16_f32 v88, v88, v89
	ds_read2_b32 v[90:91], v85 offset0:174 offset1:239
	s_waitcnt lgkmcnt(0)
	v_cvt_pk_bf16_f32 v89, v90, v91
	v_or_b32_e32 v90, s42, v78
	v_cmp_gt_i32_e32 vcc, s16, v90
	s_and_b64 vcc, s[40:41], vcc
	v_or_b32_e32 v91, s42, v79
	v_cndmask_b32_e32 v90, v90, v91, vcc
	v_mul_hi_i32_i24_e32 v91, s6, v90
	v_mul_i32_i24_e32 v90, s6, v90
	v_lshl_add_u64 v[90:91], v[90:91], 1, s[2:3]
	v_lshl_add_u64 v[90:91], v[90:91], 0, s[38:39]
	v_lshl_add_u64 v[90:91], v[90:91], 0, v[64:65]
	global_store_dwordx4 v[90:91], v[86:89], off sc1
	ds_read2_b32 v[86:87], v69 offset0:48 offset1:113
	s_waitcnt lgkmcnt(0)
	v_cvt_pk_bf16_f32 v86, v86, v87
	ds_read2_b32 v[88:89], v69 offset0:178 offset1:243
	s_waitcnt lgkmcnt(0)
	v_cvt_pk_bf16_f32 v87, v88, v89
	ds_read2_b32 v[88:89], v85 offset0:52 offset1:117
	s_waitcnt lgkmcnt(0)
	v_cvt_pk_bf16_f32 v88, v88, v89
	ds_read2_b32 v[90:91], v85 offset0:182 offset1:247
	s_waitcnt lgkmcnt(0)
	v_cvt_pk_bf16_f32 v89, v90, v91
	v_or_b32_e32 v90, s42, v80
	v_cmp_gt_i32_e32 vcc, s16, v90
	s_and_b64 vcc, s[40:41], vcc
	v_or_b32_e32 v91, s42, v81
	v_cndmask_b32_e32 v90, v90, v91, vcc
	v_mul_hi_i32_i24_e32 v91, s6, v90
	v_mul_i32_i24_e32 v90, s6, v90
	v_lshl_add_u64 v[90:91], v[90:91], 1, s[2:3]
	v_lshl_add_u64 v[90:91], v[90:91], 0, s[38:39]
	v_lshl_add_u64 v[90:91], v[90:91], 0, v[64:65]
	global_store_dwordx4 v[90:91], v[86:89], off sc1
	ds_read2_b32 v[86:87], v69 offset0:56 offset1:121
	s_waitcnt lgkmcnt(0)
	v_cvt_pk_bf16_f32 v86, v86, v87
	ds_read2_b32 v[88:89], v69 offset0:186 offset1:251
	s_waitcnt lgkmcnt(0)
	v_cvt_pk_bf16_f32 v87, v88, v89
	ds_read2_b32 v[88:89], v85 offset0:60 offset1:125
	s_waitcnt lgkmcnt(0)
	v_cvt_pk_bf16_f32 v88, v88, v89
	ds_read2_b32 v[90:91], v85 offset0:190 offset1:255
	v_or_b32_e32 v85, s42, v82
	v_cmp_gt_i32_e32 vcc, s16, v85
	s_waitcnt lgkmcnt(0)
	v_cvt_pk_bf16_f32 v89, v90, v91
	s_and_b64 vcc, s[40:41], vcc
	v_or_b32_e32 v90, s42, v83
	v_cndmask_b32_e32 v85, v85, v90, vcc
	v_mul_hi_i32_i24_e32 v91, s6, v85
	v_mul_i32_i24_e32 v90, s6, v85
	v_lshl_add_u64 v[90:91], v[90:91], 1, s[2:3]
	v_lshl_add_u64 v[90:91], v[90:91], 0, s[38:39]
	v_lshl_add_u64 v[90:91], v[90:91], 0, v[64:65]
	global_store_dwordx4 v[90:91], v[86:89], off sc1
	s_waitcnt lgkmcnt(0)
	s_add_i32 s2, s46, s47
	s_cmpk_gt_i32 s2, 0xdff
	s_mov_b64 s[2:3], s[34:35]
	s_mov_b64 s[6:7], s[36:37]
	s_mov_b32 s38, s8
	s_cbranch_scc1 .LBB0_2043
